# P1 rmsnorm+modulate rows hand-written: params loaded once per wave, contiguous 16-row blocks, 4 rows in flight
# speedup vs baseline: 1.0148x; 1.0148x over previous
; __device__ __forceinline__ unsigned cvt_pk_bf16(float lo, float hi) { unsigned r; asm volatile("v_cvt_pk_bf16_f32 %0, %1, %2" : "=v"(r) : "v"(lo), "v"(hi)); return r; }
; __device__ __forceinline__ void p1_rows(const Args& A, int lane, int wave) {
;     ...
;     for (int m = gw; m < M; m += NGW) {
;         const int b = m >> 13;
;         f32x4 v[4]; float s = 0.f;
; #pragma unroll
;         for (int j = 0; j < 4; ++j) v[j] = nx[j];
;         if (m + NGW < M) {
; #pragma unroll
;             for (int j = 0; j < 4; ++j) nx[j] = ((const f32x4*)(A.x + (size_t)(m + NGW) * DM) + lane)[64 * j]; }
; #pragma unroll
;         for (int j = 0; j < 4; ++j) s += (v[j][0] * v[j][0] + v[j][1] * v[j][1]) + (v[j][2] * v[j][2] + v[j][3] * v[j][3]);
;         const float rstd = 1.0f / sqrtf(wave_sum(s) * (1.0f / DM) + RMS_EPS);
;         u32x2* o8 = (u32x2*)(HB + (size_t)m * DM) + lane;
; #pragma unroll
;         for (int j = 0; j < 4; ++j) { const int c = 4 * lane + 256 * j;
;             const f32x4 g = *(const f32x4*)(A.g_ffn1 + c), sc = *(const f32x4*)(mods + (size_t)b * NMODC + MOD_SC1 * DM + c), sh = *(const f32x4*)(mods + (size_t)b * NMODC + MOD_SH1 * DM + c);
;             const f32x4 h = (v[j] * rstd) * g * (sc + 1.0f) + sh;
;             u32x2 w; w.x = pg8::cvt_pk_bf16(h[0], h[1]); w.y = pg8::cvt_pk_bf16(h[2], h[3]); o8[64 * j] = w; }
.LBB0_137:
	s_cmp_lt_i32 s48, 2
	s_cselect_b64 s[2:3], -1, 0
	s_and_b64 s[2:3], s[2:3], s[0:1]
	s_andn2_b64 vcc, exec, s[2:3]
	s_cbranch_vccnz .LBB0_148
	v_readlane_b32 s0, v254, 1
	v_readlane_b32 s1, v254, 2
	s_load_dwordx2 s[4:5], s[0:1], 0x98
	s_lshl_b32 s0, s87, 3
	v_readlane_b32 s1, v254, 7
	s_add_i32 s6, s1, s0
	s_lshl_b32 s8, s33, 3
	s_cmpk_gt_i32 s6, 0x7fff
	v_lshlrev_b32_e32 v34, 3, v220
	s_cbranch_scc1 .LBB0_143
	v_readlane_b32 s10, v254, 1
	v_readlane_b32 s11, v254, 2
	s_nop 0
	s_load_dwordx2 s[0:1], s[10:11], 0x0
	s_load_dwordx2 s[12:13], s[10:11], 0x20
	v_lshlrev_b32_e32 v200, 4, v220
	v_xor_b32_e32 v201, 16, v220
	v_xor_b32_e32 v202, 32, v220
	v_lshlrev_b32_e32 v201, 2, v201
	v_lshlrev_b32_e32 v202, 2, v202
	v_mov_b32_e32 v203, 0x260
	v_mov_b32_e32 v204, 0x358637bd
	s_mov_b32 s20, 0xf800000
	s_waitcnt lgkmcnt(0)
	s_lshl_b32 s7, s6, 16
	s_add_u32 s14, s0, s7
	s_addc_u32 s15, s1, 0
	s_lshl_b32 s7, s6, 15
	s_add_u32 s16, s4, 0x4000000
	s_addc_u32 s17, s5, 0
	s_add_u32 s16, s16, s7
	s_addc_u32 s17, s17, 0
	s_lshr_b32 s7, s6, 9
	s_mul_i32 s7, s7, 0x9000
	s_add_u32 s18, s4, s7
	s_addc_u32 s19, s5, 0
	s_add_u32 s22, s18, 0x1000
	s_addc_u32 s23, s19, 0
	global_load_dwordx4 v[64:67], v200, s[12:13]
	global_load_dwordx4 v[68:71], v200, s[12:13] offset:1024
	global_load_dwordx4 v[72:75], v200, s[12:13] offset:2048
	global_load_dwordx4 v[76:79], v200, s[12:13] offset:3072
	global_load_dwordx4 v[80:83], v200, s[22:23]
	global_load_dwordx4 v[84:87], v200, s[22:23] offset:1024
	global_load_dwordx4 v[88:91], v200, s[22:23] offset:2048
	global_load_dwordx4 v[92:95], v200, s[22:23] offset:3072
	global_load_dwordx4 v[96:99], v200, s[18:19]
	global_load_dwordx4 v[100:103], v200, s[18:19] offset:1024
	global_load_dwordx4 v[104:107], v200, s[18:19] offset:2048
	global_load_dwordx4 v[108:111], v200, s[18:19] offset:3072
	global_load_dwordx4 v[112:115], v200, s[14:15]
	global_load_dwordx4 v[116:119], v200, s[14:15] offset:1024
	global_load_dwordx4 v[120:123], v200, s[14:15] offset:2048
	global_load_dwordx4 v[124:127], v200, s[14:15] offset:3072
	s_add_u32 s14, s14, 0x1000
	s_addc_u32 s15, s15, 0
	global_load_dwordx4 v[128:131], v200, s[14:15]
	global_load_dwordx4 v[132:135], v200, s[14:15] offset:1024
	global_load_dwordx4 v[136:139], v200, s[14:15] offset:2048
	global_load_dwordx4 v[140:143], v200, s[14:15] offset:3072
	s_add_u32 s14, s14, 0x1000
	s_addc_u32 s15, s15, 0
	global_load_dwordx4 v[144:147], v200, s[14:15]
	global_load_dwordx4 v[148:151], v200, s[14:15] offset:1024
	global_load_dwordx4 v[152:155], v200, s[14:15] offset:2048
	global_load_dwordx4 v[156:159], v200, s[14:15] offset:3072
	s_add_u32 s14, s14, 0x1000
	s_addc_u32 s15, s15, 0
	global_load_dwordx4 v[160:163], v200, s[14:15]
	global_load_dwordx4 v[164:167], v200, s[14:15] offset:1024
	global_load_dwordx4 v[168:171], v200, s[14:15] offset:2048
	global_load_dwordx4 v[172:175], v200, s[14:15] offset:3072
	s_add_u32 s14, s14, 0x1000
	s_addc_u32 s15, s15, 0
	s_waitcnt vmcnt(12)
	v_pk_add_f32 v[80:81], v[80:81], 1.0 op_sel_hi:[1,0]
	v_pk_add_f32 v[82:83], v[82:83], 1.0 op_sel_hi:[1,0]
	v_pk_add_f32 v[84:85], v[84:85], 1.0 op_sel_hi:[1,0]
	v_pk_add_f32 v[86:87], v[86:87], 1.0 op_sel_hi:[1,0]
	v_pk_add_f32 v[88:89], v[88:89], 1.0 op_sel_hi:[1,0]
	v_pk_add_f32 v[90:91], v[90:91], 1.0 op_sel_hi:[1,0]
	v_pk_add_f32 v[92:93], v[92:93], 1.0 op_sel_hi:[1,0]
	v_pk_add_f32 v[94:95], v[94:95], 1.0 op_sel_hi:[1,0]
	v_mul_f32_e32 v177, v112, v112
	v_mul_f32_e32 v178, v114, v114
	v_fmac_f32_e32 v177, v113, v113
	v_fmac_f32_e32 v178, v115, v115
	v_add_f32_e32 v176, v177, v178
	v_mul_f32_e32 v177, v116, v116
	v_mul_f32_e32 v178, v118, v118
	v_fmac_f32_e32 v177, v117, v117
	v_fmac_f32_e32 v178, v119, v119
	v_add_f32_e32 v177, v177, v178
	v_add_f32_e32 v176, v176, v177
	v_mul_f32_e32 v177, v120, v120
	v_mul_f32_e32 v178, v122, v122
	v_fmac_f32_e32 v177, v121, v121
	v_fmac_f32_e32 v178, v123, v123
	v_add_f32_e32 v177, v177, v178
	v_add_f32_e32 v176, v176, v177
	v_mul_f32_e32 v177, v124, v124
	v_mul_f32_e32 v178, v126, v126
	v_fmac_f32_e32 v177, v125, v125
	v_fmac_f32_e32 v178, v127, v127
	v_add_f32_e32 v177, v177, v178
	v_add_f32_e32 v176, v176, v177
	s_nop 1
	v_add_f32_dpp v176, v176, v176 quad_perm:[1,0,3,2] row_mask:0xf bank_mask:0xf
	s_nop 1
	v_add_f32_dpp v176, v176, v176 quad_perm:[2,3,0,1] row_mask:0xf bank_mask:0xf
	s_nop 1
	v_add_f32_dpp v176, v176, v176 row_half_mirror row_mask:0xf bank_mask:0xf
	s_nop 1
	v_add_f32_dpp v176, v176, v176 row_mirror row_mask:0xf bank_mask:0xf
	ds_bpermute_b32 v177, v201, v176
	s_waitcnt lgkmcnt(0)
	v_add_f32_e32 v176, v176, v177
	ds_bpermute_b32 v177, v202, v176
	s_waitcnt lgkmcnt(0)
; __device__ __forceinline__ unsigned cvt_pk_bf16(float lo, float hi) { unsigned r; asm volatile("v_cvt_pk_bf16_f32 %0, %1, %2" : "=v"(r) : "v"(lo), "v"(hi)); return r; }
; __device__ __forceinline__ void p1_rows(const Args& A, int lane, int wave) {
;     ...
;         for (int j = 0; j < 4; ++j) s += (v[j][0] * v[j][0] + v[j][1] * v[j][1]) + (v[j][2] * v[j][2] + v[j][3] * v[j][3]);
;         const float rstd = 1.0f / sqrtf(wave_sum(s) * (1.0f / DM) + RMS_EPS);
;         u32x2* o8 = (u32x2*)(HB + (size_t)m * DM) + lane;
; #pragma unroll
;         for (int j = 0; j < 4; ++j) { const int c = 4 * lane + 256 * j;
;             const f32x4 g = *(const f32x4*)(A.g_ffn1 + c), sc = *(const f32x4*)(mods + (size_t)b * NMODC + MOD_SC1 * DM + c), sh = *(const f32x4*)(mods + (size_t)b * NMODC + MOD_SH1 * DM + c);
;             const f32x4 h = (v[j] * rstd) * g * (sc + 1.0f) + sh;
;             u32x2 w; w.x = pg8::cvt_pk_bf16(h[0], h[1]); w.y = pg8::cvt_pk_bf16(h[2], h[3]); o8[64 * j] = w; }
	v_add_f32_e32 v176, v176, v177
	v_fmamk_f32 v176, v176, 0x3a800000, v204
	v_mul_f32_e32 v179, 0x4f800000, v176
	v_cmp_gt_f32_e32 vcc, s20, v176
	s_nop 1
	v_cndmask_b32_e32 v176, v176, v179, vcc
	v_sqrt_f32_e32 v179, v176
	s_nop 0
	v_add_u32_e32 v180, -1, v179
	v_add_u32_e32 v181, 1, v179
	v_fma_f32 v182, -v180, v179, v176
	v_fma_f32 v183, -v181, v179, v176
	v_cmp_ge_f32_e64 s[0:1], 0, v182
	s_nop 1
	v_cndmask_b32_e64 v179, v179, v180, s[0:1]
	v_cmp_lt_f32_e64 s[0:1], 0, v183
	s_nop 1
	v_cndmask_b32_e64 v179, v179, v181, s[0:1]
	v_mul_f32_e32 v180, 0x37800000, v179
	v_cndmask_b32_e32 v179, v179, v180, vcc
	v_cmp_class_f32_e32 vcc, v176, v203
	s_nop 1
	v_cndmask_b32_e32 v176, v179, v176, vcc
	v_div_scale_f32 v179, s[0:1], v176, v176, 1.0
	v_rcp_f32_e32 v180, v179
	v_div_scale_f32 v181, vcc, 1.0, v176, 1.0
	v_fma_f32 v182, -v179, v180, 1.0
	v_fmac_f32_e32 v180, v182, v180
	v_mul_f32_e32 v182, v181, v180
	v_fma_f32 v183, -v179, v182, v181
	v_fmac_f32_e32 v182, v183, v180
	v_fma_f32 v179, -v179, v182, v181
	v_div_fmas_f32 v179, v179, v180, v182
	v_div_fixup_f32 v206, v179, v176, 1.0
	v_pk_mul_f32 v[112:113], v[112:113], v[206:207] op_sel_hi:[1,0]
	v_pk_mul_f32 v[114:115], v[114:115], v[206:207] op_sel_hi:[1,0]
	v_pk_mul_f32 v[112:113], v[64:65], v[112:113]
	v_pk_mul_f32 v[114:115], v[66:67], v[114:115]
	v_pk_fma_f32 v[112:113], v[80:81], v[112:113], v[96:97]
	v_pk_fma_f32 v[114:115], v[82:83], v[114:115], v[98:99]
	v_cvt_pk_bf16_f32 v184, v112, v113
	v_cvt_pk_bf16_f32 v185, v114, v115
	global_store_dwordx2 v34, v[184:185], s[16:17]
	v_pk_mul_f32 v[116:117], v[116:117], v[206:207] op_sel_hi:[1,0]
	v_pk_mul_f32 v[118:119], v[118:119], v[206:207] op_sel_hi:[1,0]
	v_pk_mul_f32 v[116:117], v[68:69], v[116:117]
	v_pk_mul_f32 v[118:119], v[70:71], v[118:119]
	v_pk_fma_f32 v[116:117], v[84:85], v[116:117], v[100:101]
	v_pk_fma_f32 v[118:119], v[86:87], v[118:119], v[102:103]
	v_cvt_pk_bf16_f32 v186, v116, v117
	v_cvt_pk_bf16_f32 v187, v118, v119
	global_store_dwordx2 v34, v[186:187], s[16:17] offset:512
	v_pk_mul_f32 v[120:121], v[120:121], v[206:207] op_sel_hi:[1,0]
	v_pk_mul_f32 v[122:123], v[122:123], v[206:207] op_sel_hi:[1,0]
	v_pk_mul_f32 v[120:121], v[72:73], v[120:121]
	v_pk_mul_f32 v[122:123], v[74:75], v[122:123]
	v_pk_fma_f32 v[120:121], v[88:89], v[120:121], v[104:105]
	v_pk_fma_f32 v[122:123], v[90:91], v[122:123], v[106:107]
	v_cvt_pk_bf16_f32 v188, v120, v121
	v_cvt_pk_bf16_f32 v189, v122, v123
	global_store_dwordx2 v34, v[188:189], s[16:17] offset:1024
	v_pk_mul_f32 v[124:125], v[124:125], v[206:207] op_sel_hi:[1,0]
	v_pk_mul_f32 v[126:127], v[126:127], v[206:207] op_sel_hi:[1,0]
	v_pk_mul_f32 v[124:125], v[76:77], v[124:125]
	v_pk_mul_f32 v[126:127], v[78:79], v[126:127]
	v_pk_fma_f32 v[124:125], v[92:93], v[124:125], v[108:109]
	v_pk_fma_f32 v[126:127], v[94:95], v[126:127], v[110:111]
	v_cvt_pk_bf16_f32 v190, v124, v125
	v_cvt_pk_bf16_f32 v191, v126, v127
	global_store_dwordx2 v34, v[190:191], s[16:17] offset:1536
	s_add_u32 s16, s16, 0x800
	s_addc_u32 s17, s17, 0
	global_load_dwordx4 v[112:115], v200, s[14:15]
	global_load_dwordx4 v[116:119], v200, s[14:15] offset:1024
	global_load_dwordx4 v[120:123], v200, s[14:15] offset:2048
	global_load_dwordx4 v[124:127], v200, s[14:15] offset:3072
	s_add_u32 s14, s14, 0x1000
	s_addc_u32 s15, s15, 0
	s_waitcnt vmcnt(16)
	v_mul_f32_e32 v177, v128, v128
	v_mul_f32_e32 v178, v130, v130
	v_fmac_f32_e32 v177, v129, v129
	v_fmac_f32_e32 v178, v131, v131
	v_add_f32_e32 v176, v177, v178
	v_mul_f32_e32 v177, v132, v132
	v_mul_f32_e32 v178, v134, v134
	v_fmac_f32_e32 v177, v133, v133
	v_fmac_f32_e32 v178, v135, v135
	v_add_f32_e32 v177, v177, v178
	v_add_f32_e32 v176, v176, v177
	v_mul_f32_e32 v177, v136, v136
	v_mul_f32_e32 v178, v138, v138
	v_fmac_f32_e32 v177, v137, v137
	v_fmac_f32_e32 v178, v139, v139
	v_add_f32_e32 v177, v177, v178
	v_add_f32_e32 v176, v176, v177
	v_mul_f32_e32 v177, v140, v140
	v_mul_f32_e32 v178, v142, v142
	v_fmac_f32_e32 v177, v141, v141
	v_fmac_f32_e32 v178, v143, v143
	v_add_f32_e32 v177, v177, v178
	v_add_f32_e32 v176, v176, v177
	s_nop 1
	v_add_f32_dpp v176, v176, v176 quad_perm:[1,0,3,2] row_mask:0xf bank_mask:0xf
	s_nop 1
	v_add_f32_dpp v176, v176, v176 quad_perm:[2,3,0,1] row_mask:0xf bank_mask:0xf
	s_nop 1
	v_add_f32_dpp v176, v176, v176 row_half_mirror row_mask:0xf bank_mask:0xf
	s_nop 1
	v_add_f32_dpp v176, v176, v176 row_mirror row_mask:0xf bank_mask:0xf
	ds_bpermute_b32 v177, v201, v176
	s_waitcnt lgkmcnt(0)
	v_add_f32_e32 v176, v176, v177
	ds_bpermute_b32 v177, v202, v176
	s_waitcnt lgkmcnt(0)
; __device__ __forceinline__ unsigned cvt_pk_bf16(float lo, float hi) { unsigned r; asm volatile("v_cvt_pk_bf16_f32 %0, %1, %2" : "=v"(r) : "v"(lo), "v"(hi)); return r; }
; __device__ __forceinline__ void p1_rows(const Args& A, int lane, int wave) {
;     ...
;         for (int j = 0; j < 4; ++j) s += (v[j][0] * v[j][0] + v[j][1] * v[j][1]) + (v[j][2] * v[j][2] + v[j][3] * v[j][3]);
;         const float rstd = 1.0f / sqrtf(wave_sum(s) * (1.0f / DM) + RMS_EPS);
;         u32x2* o8 = (u32x2*)(HB + (size_t)m * DM) + lane;
; #pragma unroll
;         for (int j = 0; j < 4; ++j) { const int c = 4 * lane + 256 * j;
;             const f32x4 g = *(const f32x4*)(A.g_ffn1 + c), sc = *(const f32x4*)(mods + (size_t)b * NMODC + MOD_SC1 * DM + c), sh = *(const f32x4*)(mods + (size_t)b * NMODC + MOD_SH1 * DM + c);
;             const f32x4 h = (v[j] * rstd) * g * (sc + 1.0f) + sh;
;             u32x2 w; w.x = pg8::cvt_pk_bf16(h[0], h[1]); w.y = pg8::cvt_pk_bf16(h[2], h[3]); o8[64 * j] = w; }
	v_add_f32_e32 v176, v176, v177
	v_fmamk_f32 v176, v176, 0x3a800000, v204
	v_mul_f32_e32 v179, 0x4f800000, v176
	v_cmp_gt_f32_e32 vcc, s20, v176
	s_nop 1
	v_cndmask_b32_e32 v176, v176, v179, vcc
	v_sqrt_f32_e32 v179, v176
	s_nop 0
	v_add_u32_e32 v180, -1, v179
	v_add_u32_e32 v181, 1, v179
	v_fma_f32 v182, -v180, v179, v176
	v_fma_f32 v183, -v181, v179, v176
	v_cmp_ge_f32_e64 s[0:1], 0, v182
	s_nop 1
	v_cndmask_b32_e64 v179, v179, v180, s[0:1]
	v_cmp_lt_f32_e64 s[0:1], 0, v183
	s_nop 1
	v_cndmask_b32_e64 v179, v179, v181, s[0:1]
	v_mul_f32_e32 v180, 0x37800000, v179
	v_cndmask_b32_e32 v179, v179, v180, vcc
	v_cmp_class_f32_e32 vcc, v176, v203
	s_nop 1
	v_cndmask_b32_e32 v176, v179, v176, vcc
	v_div_scale_f32 v179, s[0:1], v176, v176, 1.0
	v_rcp_f32_e32 v180, v179
	v_div_scale_f32 v181, vcc, 1.0, v176, 1.0
	v_fma_f32 v182, -v179, v180, 1.0
	v_fmac_f32_e32 v180, v182, v180
	v_mul_f32_e32 v182, v181, v180
	v_fma_f32 v183, -v179, v182, v181
	v_fmac_f32_e32 v182, v183, v180
	v_fma_f32 v179, -v179, v182, v181
	v_div_fmas_f32 v179, v179, v180, v182
	v_div_fixup_f32 v206, v179, v176, 1.0
	v_pk_mul_f32 v[128:129], v[128:129], v[206:207] op_sel_hi:[1,0]
	v_pk_mul_f32 v[130:131], v[130:131], v[206:207] op_sel_hi:[1,0]
	v_pk_mul_f32 v[128:129], v[64:65], v[128:129]
	v_pk_mul_f32 v[130:131], v[66:67], v[130:131]
	v_pk_fma_f32 v[128:129], v[80:81], v[128:129], v[96:97]
	v_pk_fma_f32 v[130:131], v[82:83], v[130:131], v[98:99]
	v_cvt_pk_bf16_f32 v192, v128, v129
	v_cvt_pk_bf16_f32 v193, v130, v131
	global_store_dwordx2 v34, v[192:193], s[16:17]
	v_pk_mul_f32 v[132:133], v[132:133], v[206:207] op_sel_hi:[1,0]
	v_pk_mul_f32 v[134:135], v[134:135], v[206:207] op_sel_hi:[1,0]
	v_pk_mul_f32 v[132:133], v[68:69], v[132:133]
	v_pk_mul_f32 v[134:135], v[70:71], v[134:135]
	v_pk_fma_f32 v[132:133], v[84:85], v[132:133], v[100:101]
	v_pk_fma_f32 v[134:135], v[86:87], v[134:135], v[102:103]
	v_cvt_pk_bf16_f32 v194, v132, v133
	v_cvt_pk_bf16_f32 v195, v134, v135
	global_store_dwordx2 v34, v[194:195], s[16:17] offset:512
	v_pk_mul_f32 v[136:137], v[136:137], v[206:207] op_sel_hi:[1,0]
	v_pk_mul_f32 v[138:139], v[138:139], v[206:207] op_sel_hi:[1,0]
	v_pk_mul_f32 v[136:137], v[72:73], v[136:137]
	v_pk_mul_f32 v[138:139], v[74:75], v[138:139]
	v_pk_fma_f32 v[136:137], v[88:89], v[136:137], v[104:105]
	v_pk_fma_f32 v[138:139], v[90:91], v[138:139], v[106:107]
	v_cvt_pk_bf16_f32 v196, v136, v137
	v_cvt_pk_bf16_f32 v197, v138, v139
	global_store_dwordx2 v34, v[196:197], s[16:17] offset:1024
	v_pk_mul_f32 v[140:141], v[140:141], v[206:207] op_sel_hi:[1,0]
	v_pk_mul_f32 v[142:143], v[142:143], v[206:207] op_sel_hi:[1,0]
	v_pk_mul_f32 v[140:141], v[76:77], v[140:141]
	v_pk_mul_f32 v[142:143], v[78:79], v[142:143]
	v_pk_fma_f32 v[140:141], v[92:93], v[140:141], v[108:109]
	v_pk_fma_f32 v[142:143], v[94:95], v[142:143], v[110:111]
	v_cvt_pk_bf16_f32 v198, v140, v141
	v_cvt_pk_bf16_f32 v199, v142, v143
	global_store_dwordx2 v34, v[198:199], s[16:17] offset:1536
	s_add_u32 s16, s16, 0x800
	s_addc_u32 s17, s17, 0
	global_load_dwordx4 v[128:131], v200, s[14:15]
	global_load_dwordx4 v[132:135], v200, s[14:15] offset:1024
	global_load_dwordx4 v[136:139], v200, s[14:15] offset:2048
	global_load_dwordx4 v[140:143], v200, s[14:15] offset:3072
	s_add_u32 s14, s14, 0x1000
	s_addc_u32 s15, s15, 0
	s_waitcnt vmcnt(20)
	v_mul_f32_e32 v177, v144, v144
	v_mul_f32_e32 v178, v146, v146
	v_fmac_f32_e32 v177, v145, v145
	v_fmac_f32_e32 v178, v147, v147
	v_add_f32_e32 v176, v177, v178
	v_mul_f32_e32 v177, v148, v148
	v_mul_f32_e32 v178, v150, v150
	v_fmac_f32_e32 v177, v149, v149
	v_fmac_f32_e32 v178, v151, v151
	v_add_f32_e32 v177, v177, v178
	v_add_f32_e32 v176, v176, v177
	v_mul_f32_e32 v177, v152, v152
	v_mul_f32_e32 v178, v154, v154
	v_fmac_f32_e32 v177, v153, v153
	v_fmac_f32_e32 v178, v155, v155
	v_add_f32_e32 v177, v177, v178
	v_add_f32_e32 v176, v176, v177
	v_mul_f32_e32 v177, v156, v156
	v_mul_f32_e32 v178, v158, v158
	v_fmac_f32_e32 v177, v157, v157
	v_fmac_f32_e32 v178, v159, v159
	v_add_f32_e32 v177, v177, v178
	v_add_f32_e32 v176, v176, v177
	s_nop 1
	v_add_f32_dpp v176, v176, v176 quad_perm:[1,0,3,2] row_mask:0xf bank_mask:0xf
	s_nop 1
	v_add_f32_dpp v176, v176, v176 quad_perm:[2,3,0,1] row_mask:0xf bank_mask:0xf
	s_nop 1
	v_add_f32_dpp v176, v176, v176 row_half_mirror row_mask:0xf bank_mask:0xf
	s_nop 1
	v_add_f32_dpp v176, v176, v176 row_mirror row_mask:0xf bank_mask:0xf
	ds_bpermute_b32 v177, v201, v176
	s_waitcnt lgkmcnt(0)
	v_add_f32_e32 v176, v176, v177
	ds_bpermute_b32 v177, v202, v176
	s_waitcnt lgkmcnt(0)
; __device__ __forceinline__ unsigned cvt_pk_bf16(float lo, float hi) { unsigned r; asm volatile("v_cvt_pk_bf16_f32 %0, %1, %2" : "=v"(r) : "v"(lo), "v"(hi)); return r; }
; __device__ __forceinline__ void p1_rows(const Args& A, int lane, int wave) {
;     ...
;         for (int j = 0; j < 4; ++j) s += (v[j][0] * v[j][0] + v[j][1] * v[j][1]) + (v[j][2] * v[j][2] + v[j][3] * v[j][3]);
;         const float rstd = 1.0f / sqrtf(wave_sum(s) * (1.0f / DM) + RMS_EPS);
;         u32x2* o8 = (u32x2*)(HB + (size_t)m * DM) + lane;
; #pragma unroll
;         for (int j = 0; j < 4; ++j) { const int c = 4 * lane + 256 * j;
;             const f32x4 g = *(const f32x4*)(A.g_ffn1 + c), sc = *(const f32x4*)(mods + (size_t)b * NMODC + MOD_SC1 * DM + c), sh = *(const f32x4*)(mods + (size_t)b * NMODC + MOD_SH1 * DM + c);
;             const f32x4 h = (v[j] * rstd) * g * (sc + 1.0f) + sh;
;             u32x2 w; w.x = pg8::cvt_pk_bf16(h[0], h[1]); w.y = pg8::cvt_pk_bf16(h[2], h[3]); o8[64 * j] = w; }
	v_add_f32_e32 v176, v176, v177
	v_fmamk_f32 v176, v176, 0x3a800000, v204
	v_mul_f32_e32 v179, 0x4f800000, v176
	v_cmp_gt_f32_e32 vcc, s20, v176
	s_nop 1
	v_cndmask_b32_e32 v176, v176, v179, vcc
	v_sqrt_f32_e32 v179, v176
	s_nop 0
	v_add_u32_e32 v180, -1, v179
	v_add_u32_e32 v181, 1, v179
	v_fma_f32 v182, -v180, v179, v176
	v_fma_f32 v183, -v181, v179, v176
	v_cmp_ge_f32_e64 s[0:1], 0, v182
	s_nop 1
	v_cndmask_b32_e64 v179, v179, v180, s[0:1]
	v_cmp_lt_f32_e64 s[0:1], 0, v183
	s_nop 1
	v_cndmask_b32_e64 v179, v179, v181, s[0:1]
	v_mul_f32_e32 v180, 0x37800000, v179
	v_cndmask_b32_e32 v179, v179, v180, vcc
	v_cmp_class_f32_e32 vcc, v176, v203
	s_nop 1
	v_cndmask_b32_e32 v176, v179, v176, vcc
	v_div_scale_f32 v179, s[0:1], v176, v176, 1.0
	v_rcp_f32_e32 v180, v179
	v_div_scale_f32 v181, vcc, 1.0, v176, 1.0
	v_fma_f32 v182, -v179, v180, 1.0
	v_fmac_f32_e32 v180, v182, v180
	v_mul_f32_e32 v182, v181, v180
	v_fma_f32 v183, -v179, v182, v181
	v_fmac_f32_e32 v182, v183, v180
	v_fma_f32 v179, -v179, v182, v181
	v_div_fmas_f32 v179, v179, v180, v182
	v_div_fixup_f32 v206, v179, v176, 1.0
	v_pk_mul_f32 v[144:145], v[144:145], v[206:207] op_sel_hi:[1,0]
	v_pk_mul_f32 v[146:147], v[146:147], v[206:207] op_sel_hi:[1,0]
	v_pk_mul_f32 v[144:145], v[64:65], v[144:145]
	v_pk_mul_f32 v[146:147], v[66:67], v[146:147]
	v_pk_fma_f32 v[144:145], v[80:81], v[144:145], v[96:97]
	v_pk_fma_f32 v[146:147], v[82:83], v[146:147], v[98:99]
	v_cvt_pk_bf16_f32 v184, v144, v145
	v_cvt_pk_bf16_f32 v185, v146, v147
	global_store_dwordx2 v34, v[184:185], s[16:17]
	v_pk_mul_f32 v[148:149], v[148:149], v[206:207] op_sel_hi:[1,0]
	v_pk_mul_f32 v[150:151], v[150:151], v[206:207] op_sel_hi:[1,0]
	v_pk_mul_f32 v[148:149], v[68:69], v[148:149]
	v_pk_mul_f32 v[150:151], v[70:71], v[150:151]
	v_pk_fma_f32 v[148:149], v[84:85], v[148:149], v[100:101]
	v_pk_fma_f32 v[150:151], v[86:87], v[150:151], v[102:103]
	v_cvt_pk_bf16_f32 v186, v148, v149
	v_cvt_pk_bf16_f32 v187, v150, v151
	global_store_dwordx2 v34, v[186:187], s[16:17] offset:512
	v_pk_mul_f32 v[152:153], v[152:153], v[206:207] op_sel_hi:[1,0]
	v_pk_mul_f32 v[154:155], v[154:155], v[206:207] op_sel_hi:[1,0]
	v_pk_mul_f32 v[152:153], v[72:73], v[152:153]
	v_pk_mul_f32 v[154:155], v[74:75], v[154:155]
	v_pk_fma_f32 v[152:153], v[88:89], v[152:153], v[104:105]
	v_pk_fma_f32 v[154:155], v[90:91], v[154:155], v[106:107]
	v_cvt_pk_bf16_f32 v188, v152, v153
	v_cvt_pk_bf16_f32 v189, v154, v155
	global_store_dwordx2 v34, v[188:189], s[16:17] offset:1024
	v_pk_mul_f32 v[156:157], v[156:157], v[206:207] op_sel_hi:[1,0]
	v_pk_mul_f32 v[158:159], v[158:159], v[206:207] op_sel_hi:[1,0]
	v_pk_mul_f32 v[156:157], v[76:77], v[156:157]
	v_pk_mul_f32 v[158:159], v[78:79], v[158:159]
	v_pk_fma_f32 v[156:157], v[92:93], v[156:157], v[108:109]
	v_pk_fma_f32 v[158:159], v[94:95], v[158:159], v[110:111]
	v_cvt_pk_bf16_f32 v190, v156, v157
	v_cvt_pk_bf16_f32 v191, v158, v159
	global_store_dwordx2 v34, v[190:191], s[16:17] offset:1536
	s_add_u32 s16, s16, 0x800
	s_addc_u32 s17, s17, 0
	global_load_dwordx4 v[144:147], v200, s[14:15]
	global_load_dwordx4 v[148:151], v200, s[14:15] offset:1024
	global_load_dwordx4 v[152:155], v200, s[14:15] offset:2048
	global_load_dwordx4 v[156:159], v200, s[14:15] offset:3072
	s_add_u32 s14, s14, 0x1000
	s_addc_u32 s15, s15, 0
	s_waitcnt vmcnt(24)
	v_mul_f32_e32 v177, v160, v160
	v_mul_f32_e32 v178, v162, v162
	v_fmac_f32_e32 v177, v161, v161
	v_fmac_f32_e32 v178, v163, v163
	v_add_f32_e32 v176, v177, v178
	v_mul_f32_e32 v177, v164, v164
	v_mul_f32_e32 v178, v166, v166
	v_fmac_f32_e32 v177, v165, v165
	v_fmac_f32_e32 v178, v167, v167
	v_add_f32_e32 v177, v177, v178
	v_add_f32_e32 v176, v176, v177
	v_mul_f32_e32 v177, v168, v168
	v_mul_f32_e32 v178, v170, v170
	v_fmac_f32_e32 v177, v169, v169
	v_fmac_f32_e32 v178, v171, v171
	v_add_f32_e32 v177, v177, v178
	v_add_f32_e32 v176, v176, v177
	v_mul_f32_e32 v177, v172, v172
	v_mul_f32_e32 v178, v174, v174
	v_fmac_f32_e32 v177, v173, v173
	v_fmac_f32_e32 v178, v175, v175
	v_add_f32_e32 v177, v177, v178
	v_add_f32_e32 v176, v176, v177
	s_nop 1
	v_add_f32_dpp v176, v176, v176 quad_perm:[1,0,3,2] row_mask:0xf bank_mask:0xf
	s_nop 1
	v_add_f32_dpp v176, v176, v176 quad_perm:[2,3,0,1] row_mask:0xf bank_mask:0xf
	s_nop 1
	v_add_f32_dpp v176, v176, v176 row_half_mirror row_mask:0xf bank_mask:0xf
	s_nop 1
	v_add_f32_dpp v176, v176, v176 row_mirror row_mask:0xf bank_mask:0xf
	ds_bpermute_b32 v177, v201, v176
	s_waitcnt lgkmcnt(0)
	v_add_f32_e32 v176, v176, v177
	ds_bpermute_b32 v177, v202, v176
	s_waitcnt lgkmcnt(0)
; __device__ __forceinline__ unsigned cvt_pk_bf16(float lo, float hi) { unsigned r; asm volatile("v_cvt_pk_bf16_f32 %0, %1, %2" : "=v"(r) : "v"(lo), "v"(hi)); return r; }
; __device__ __forceinline__ void p1_rows(const Args& A, int lane, int wave) {
;     ...
;         for (int j = 0; j < 4; ++j) s += (v[j][0] * v[j][0] + v[j][1] * v[j][1]) + (v[j][2] * v[j][2] + v[j][3] * v[j][3]);
;         const float rstd = 1.0f / sqrtf(wave_sum(s) * (1.0f / DM) + RMS_EPS);
;         u32x2* o8 = (u32x2*)(HB + (size_t)m * DM) + lane;
; #pragma unroll
;         for (int j = 0; j < 4; ++j) { const int c = 4 * lane + 256 * j;
;             const f32x4 g = *(const f32x4*)(A.g_ffn1 + c), sc = *(const f32x4*)(mods + (size_t)b * NMODC + MOD_SC1 * DM + c), sh = *(const f32x4*)(mods + (size_t)b * NMODC + MOD_SH1 * DM + c);
;             const f32x4 h = (v[j] * rstd) * g * (sc + 1.0f) + sh;
;             u32x2 w; w.x = pg8::cvt_pk_bf16(h[0], h[1]); w.y = pg8::cvt_pk_bf16(h[2], h[3]); o8[64 * j] = w; }
	v_add_f32_e32 v176, v176, v177
	v_fmamk_f32 v176, v176, 0x3a800000, v204
	v_mul_f32_e32 v179, 0x4f800000, v176
	v_cmp_gt_f32_e32 vcc, s20, v176
	s_nop 1
	v_cndmask_b32_e32 v176, v176, v179, vcc
	v_sqrt_f32_e32 v179, v176
	s_nop 0
	v_add_u32_e32 v180, -1, v179
	v_add_u32_e32 v181, 1, v179
	v_fma_f32 v182, -v180, v179, v176
	v_fma_f32 v183, -v181, v179, v176
	v_cmp_ge_f32_e64 s[0:1], 0, v182
	s_nop 1
	v_cndmask_b32_e64 v179, v179, v180, s[0:1]
	v_cmp_lt_f32_e64 s[0:1], 0, v183
	s_nop 1
	v_cndmask_b32_e64 v179, v179, v181, s[0:1]
	v_mul_f32_e32 v180, 0x37800000, v179
	v_cndmask_b32_e32 v179, v179, v180, vcc
	v_cmp_class_f32_e32 vcc, v176, v203
	s_nop 1
	v_cndmask_b32_e32 v176, v179, v176, vcc
	v_div_scale_f32 v179, s[0:1], v176, v176, 1.0
	v_rcp_f32_e32 v180, v179
	v_div_scale_f32 v181, vcc, 1.0, v176, 1.0
	v_fma_f32 v182, -v179, v180, 1.0
	v_fmac_f32_e32 v180, v182, v180
	v_mul_f32_e32 v182, v181, v180
	v_fma_f32 v183, -v179, v182, v181
	v_fmac_f32_e32 v182, v183, v180
	v_fma_f32 v179, -v179, v182, v181
	v_div_fmas_f32 v179, v179, v180, v182
	v_div_fixup_f32 v206, v179, v176, 1.0
	v_pk_mul_f32 v[160:161], v[160:161], v[206:207] op_sel_hi:[1,0]
	v_pk_mul_f32 v[162:163], v[162:163], v[206:207] op_sel_hi:[1,0]
	v_pk_mul_f32 v[160:161], v[64:65], v[160:161]
	v_pk_mul_f32 v[162:163], v[66:67], v[162:163]
	v_pk_fma_f32 v[160:161], v[80:81], v[160:161], v[96:97]
	v_pk_fma_f32 v[162:163], v[82:83], v[162:163], v[98:99]
	v_cvt_pk_bf16_f32 v192, v160, v161
	v_cvt_pk_bf16_f32 v193, v162, v163
	global_store_dwordx2 v34, v[192:193], s[16:17]
	v_pk_mul_f32 v[164:165], v[164:165], v[206:207] op_sel_hi:[1,0]
	v_pk_mul_f32 v[166:167], v[166:167], v[206:207] op_sel_hi:[1,0]
	v_pk_mul_f32 v[164:165], v[68:69], v[164:165]
	v_pk_mul_f32 v[166:167], v[70:71], v[166:167]
	v_pk_fma_f32 v[164:165], v[84:85], v[164:165], v[100:101]
	v_pk_fma_f32 v[166:167], v[86:87], v[166:167], v[102:103]
	v_cvt_pk_bf16_f32 v194, v164, v165
	v_cvt_pk_bf16_f32 v195, v166, v167
	global_store_dwordx2 v34, v[194:195], s[16:17] offset:512
	v_pk_mul_f32 v[168:169], v[168:169], v[206:207] op_sel_hi:[1,0]
	v_pk_mul_f32 v[170:171], v[170:171], v[206:207] op_sel_hi:[1,0]
	v_pk_mul_f32 v[168:169], v[72:73], v[168:169]
	v_pk_mul_f32 v[170:171], v[74:75], v[170:171]
	v_pk_fma_f32 v[168:169], v[88:89], v[168:169], v[104:105]
	v_pk_fma_f32 v[170:171], v[90:91], v[170:171], v[106:107]
	v_cvt_pk_bf16_f32 v196, v168, v169
	v_cvt_pk_bf16_f32 v197, v170, v171
	global_store_dwordx2 v34, v[196:197], s[16:17] offset:1024
	v_pk_mul_f32 v[172:173], v[172:173], v[206:207] op_sel_hi:[1,0]
	v_pk_mul_f32 v[174:175], v[174:175], v[206:207] op_sel_hi:[1,0]
	v_pk_mul_f32 v[172:173], v[76:77], v[172:173]
	v_pk_mul_f32 v[174:175], v[78:79], v[174:175]
	v_pk_fma_f32 v[172:173], v[92:93], v[172:173], v[108:109]
	v_pk_fma_f32 v[174:175], v[94:95], v[174:175], v[110:111]
	v_cvt_pk_bf16_f32 v198, v172, v173
	v_cvt_pk_bf16_f32 v199, v174, v175
	global_store_dwordx2 v34, v[198:199], s[16:17] offset:1536
	s_add_u32 s16, s16, 0x800
	s_addc_u32 s17, s17, 0
	global_load_dwordx4 v[160:163], v200, s[14:15]
	global_load_dwordx4 v[164:167], v200, s[14:15] offset:1024
	global_load_dwordx4 v[168:171], v200, s[14:15] offset:2048
	global_load_dwordx4 v[172:175], v200, s[14:15] offset:3072
	s_add_u32 s14, s14, 0x1000
	s_addc_u32 s15, s15, 0
	s_waitcnt vmcnt(24)
	v_mul_f32_e32 v177, v112, v112
	v_mul_f32_e32 v178, v114, v114
	v_fmac_f32_e32 v177, v113, v113
	v_fmac_f32_e32 v178, v115, v115
	v_add_f32_e32 v176, v177, v178
	v_mul_f32_e32 v177, v116, v116
	v_mul_f32_e32 v178, v118, v118
	v_fmac_f32_e32 v177, v117, v117
	v_fmac_f32_e32 v178, v119, v119
	v_add_f32_e32 v177, v177, v178
	v_add_f32_e32 v176, v176, v177
	v_mul_f32_e32 v177, v120, v120
	v_mul_f32_e32 v178, v122, v122
	v_fmac_f32_e32 v177, v121, v121
	v_fmac_f32_e32 v178, v123, v123
	v_add_f32_e32 v177, v177, v178
	v_add_f32_e32 v176, v176, v177
	v_mul_f32_e32 v177, v124, v124
	v_mul_f32_e32 v178, v126, v126
	v_fmac_f32_e32 v177, v125, v125
	v_fmac_f32_e32 v178, v127, v127
	v_add_f32_e32 v177, v177, v178
	v_add_f32_e32 v176, v176, v177
	s_nop 1
	v_add_f32_dpp v176, v176, v176 quad_perm:[1,0,3,2] row_mask:0xf bank_mask:0xf
	s_nop 1
	v_add_f32_dpp v176, v176, v176 quad_perm:[2,3,0,1] row_mask:0xf bank_mask:0xf
	s_nop 1
	v_add_f32_dpp v176, v176, v176 row_half_mirror row_mask:0xf bank_mask:0xf
	s_nop 1
	v_add_f32_dpp v176, v176, v176 row_mirror row_mask:0xf bank_mask:0xf
	ds_bpermute_b32 v177, v201, v176
	s_waitcnt lgkmcnt(0)
	v_add_f32_e32 v176, v176, v177
	ds_bpermute_b32 v177, v202, v176
	s_waitcnt lgkmcnt(0)
; __device__ __forceinline__ unsigned cvt_pk_bf16(float lo, float hi) { unsigned r; asm volatile("v_cvt_pk_bf16_f32 %0, %1, %2" : "=v"(r) : "v"(lo), "v"(hi)); return r; }
; __device__ __forceinline__ void p1_rows(const Args& A, int lane, int wave) {
;     ...
;         for (int j = 0; j < 4; ++j) s += (v[j][0] * v[j][0] + v[j][1] * v[j][1]) + (v[j][2] * v[j][2] + v[j][3] * v[j][3]);
;         const float rstd = 1.0f / sqrtf(wave_sum(s) * (1.0f / DM) + RMS_EPS);
;         u32x2* o8 = (u32x2*)(HB + (size_t)m * DM) + lane;
; #pragma unroll
;         for (int j = 0; j < 4; ++j) { const int c = 4 * lane + 256 * j;
;             const f32x4 g = *(const f32x4*)(A.g_ffn1 + c), sc = *(const f32x4*)(mods + (size_t)b * NMODC + MOD_SC1 * DM + c), sh = *(const f32x4*)(mods + (size_t)b * NMODC + MOD_SH1 * DM + c);
;             const f32x4 h = (v[j] * rstd) * g * (sc + 1.0f) + sh;
;             u32x2 w; w.x = pg8::cvt_pk_bf16(h[0], h[1]); w.y = pg8::cvt_pk_bf16(h[2], h[3]); o8[64 * j] = w; }
	v_add_f32_e32 v176, v176, v177
	v_fmamk_f32 v176, v176, 0x3a800000, v204
	v_mul_f32_e32 v179, 0x4f800000, v176
	v_cmp_gt_f32_e32 vcc, s20, v176
	s_nop 1
	v_cndmask_b32_e32 v176, v176, v179, vcc
	v_sqrt_f32_e32 v179, v176
	s_nop 0
	v_add_u32_e32 v180, -1, v179
	v_add_u32_e32 v181, 1, v179
	v_fma_f32 v182, -v180, v179, v176
	v_fma_f32 v183, -v181, v179, v176
	v_cmp_ge_f32_e64 s[0:1], 0, v182
	s_nop 1
	v_cndmask_b32_e64 v179, v179, v180, s[0:1]
	v_cmp_lt_f32_e64 s[0:1], 0, v183
	s_nop 1
	v_cndmask_b32_e64 v179, v179, v181, s[0:1]
	v_mul_f32_e32 v180, 0x37800000, v179
	v_cndmask_b32_e32 v179, v179, v180, vcc
	v_cmp_class_f32_e32 vcc, v176, v203
	s_nop 1
	v_cndmask_b32_e32 v176, v179, v176, vcc
	v_div_scale_f32 v179, s[0:1], v176, v176, 1.0
	v_rcp_f32_e32 v180, v179
	v_div_scale_f32 v181, vcc, 1.0, v176, 1.0
	v_fma_f32 v182, -v179, v180, 1.0
	v_fmac_f32_e32 v180, v182, v180
	v_mul_f32_e32 v182, v181, v180
	v_fma_f32 v183, -v179, v182, v181
	v_fmac_f32_e32 v182, v183, v180
	v_fma_f32 v179, -v179, v182, v181
	v_div_fmas_f32 v179, v179, v180, v182
	v_div_fixup_f32 v206, v179, v176, 1.0
	v_pk_mul_f32 v[112:113], v[112:113], v[206:207] op_sel_hi:[1,0]
	v_pk_mul_f32 v[114:115], v[114:115], v[206:207] op_sel_hi:[1,0]
	v_pk_mul_f32 v[112:113], v[64:65], v[112:113]
	v_pk_mul_f32 v[114:115], v[66:67], v[114:115]
	v_pk_fma_f32 v[112:113], v[80:81], v[112:113], v[96:97]
	v_pk_fma_f32 v[114:115], v[82:83], v[114:115], v[98:99]
	v_cvt_pk_bf16_f32 v184, v112, v113
	v_cvt_pk_bf16_f32 v185, v114, v115
	global_store_dwordx2 v34, v[184:185], s[16:17]
	v_pk_mul_f32 v[116:117], v[116:117], v[206:207] op_sel_hi:[1,0]
	v_pk_mul_f32 v[118:119], v[118:119], v[206:207] op_sel_hi:[1,0]
	v_pk_mul_f32 v[116:117], v[68:69], v[116:117]
	v_pk_mul_f32 v[118:119], v[70:71], v[118:119]
	v_pk_fma_f32 v[116:117], v[84:85], v[116:117], v[100:101]
	v_pk_fma_f32 v[118:119], v[86:87], v[118:119], v[102:103]
	v_cvt_pk_bf16_f32 v186, v116, v117
	v_cvt_pk_bf16_f32 v187, v118, v119
	global_store_dwordx2 v34, v[186:187], s[16:17] offset:512
	v_pk_mul_f32 v[120:121], v[120:121], v[206:207] op_sel_hi:[1,0]
	v_pk_mul_f32 v[122:123], v[122:123], v[206:207] op_sel_hi:[1,0]
	v_pk_mul_f32 v[120:121], v[72:73], v[120:121]
	v_pk_mul_f32 v[122:123], v[74:75], v[122:123]
	v_pk_fma_f32 v[120:121], v[88:89], v[120:121], v[104:105]
	v_pk_fma_f32 v[122:123], v[90:91], v[122:123], v[106:107]
	v_cvt_pk_bf16_f32 v188, v120, v121
	v_cvt_pk_bf16_f32 v189, v122, v123
	global_store_dwordx2 v34, v[188:189], s[16:17] offset:1024
	v_pk_mul_f32 v[124:125], v[124:125], v[206:207] op_sel_hi:[1,0]
	v_pk_mul_f32 v[126:127], v[126:127], v[206:207] op_sel_hi:[1,0]
	v_pk_mul_f32 v[124:125], v[76:77], v[124:125]
	v_pk_mul_f32 v[126:127], v[78:79], v[126:127]
	v_pk_fma_f32 v[124:125], v[92:93], v[124:125], v[108:109]
	v_pk_fma_f32 v[126:127], v[94:95], v[126:127], v[110:111]
	v_cvt_pk_bf16_f32 v190, v124, v125
	v_cvt_pk_bf16_f32 v191, v126, v127
	global_store_dwordx2 v34, v[190:191], s[16:17] offset:1536
	s_add_u32 s16, s16, 0x800
	s_addc_u32 s17, s17, 0
	global_load_dwordx4 v[112:115], v200, s[14:15]
	global_load_dwordx4 v[116:119], v200, s[14:15] offset:1024
	global_load_dwordx4 v[120:123], v200, s[14:15] offset:2048
	global_load_dwordx4 v[124:127], v200, s[14:15] offset:3072
	s_add_u32 s14, s14, 0x1000
	s_addc_u32 s15, s15, 0
	s_waitcnt vmcnt(24)
	v_mul_f32_e32 v177, v128, v128
	v_mul_f32_e32 v178, v130, v130
	v_fmac_f32_e32 v177, v129, v129
	v_fmac_f32_e32 v178, v131, v131
	v_add_f32_e32 v176, v177, v178
	v_mul_f32_e32 v177, v132, v132
	v_mul_f32_e32 v178, v134, v134
	v_fmac_f32_e32 v177, v133, v133
	v_fmac_f32_e32 v178, v135, v135
	v_add_f32_e32 v177, v177, v178
	v_add_f32_e32 v176, v176, v177
	v_mul_f32_e32 v177, v136, v136
	v_mul_f32_e32 v178, v138, v138
	v_fmac_f32_e32 v177, v137, v137
	v_fmac_f32_e32 v178, v139, v139
	v_add_f32_e32 v177, v177, v178
	v_add_f32_e32 v176, v176, v177
	v_mul_f32_e32 v177, v140, v140
	v_mul_f32_e32 v178, v142, v142
	v_fmac_f32_e32 v177, v141, v141
	v_fmac_f32_e32 v178, v143, v143
	v_add_f32_e32 v177, v177, v178
	v_add_f32_e32 v176, v176, v177
	s_nop 1
	v_add_f32_dpp v176, v176, v176 quad_perm:[1,0,3,2] row_mask:0xf bank_mask:0xf
	s_nop 1
	v_add_f32_dpp v176, v176, v176 quad_perm:[2,3,0,1] row_mask:0xf bank_mask:0xf
	s_nop 1
	v_add_f32_dpp v176, v176, v176 row_half_mirror row_mask:0xf bank_mask:0xf
	s_nop 1
	v_add_f32_dpp v176, v176, v176 row_mirror row_mask:0xf bank_mask:0xf
	ds_bpermute_b32 v177, v201, v176
	s_waitcnt lgkmcnt(0)
	v_add_f32_e32 v176, v176, v177
	ds_bpermute_b32 v177, v202, v176
	s_waitcnt lgkmcnt(0)
; __device__ __forceinline__ unsigned cvt_pk_bf16(float lo, float hi) { unsigned r; asm volatile("v_cvt_pk_bf16_f32 %0, %1, %2" : "=v"(r) : "v"(lo), "v"(hi)); return r; }
; __device__ __forceinline__ void p1_rows(const Args& A, int lane, int wave) {
;     ...
;         for (int j = 0; j < 4; ++j) s += (v[j][0] * v[j][0] + v[j][1] * v[j][1]) + (v[j][2] * v[j][2] + v[j][3] * v[j][3]);
;         const float rstd = 1.0f / sqrtf(wave_sum(s) * (1.0f / DM) + RMS_EPS);
;         u32x2* o8 = (u32x2*)(HB + (size_t)m * DM) + lane;
; #pragma unroll
;         for (int j = 0; j < 4; ++j) { const int c = 4 * lane + 256 * j;
;             const f32x4 g = *(const f32x4*)(A.g_ffn1 + c), sc = *(const f32x4*)(mods + (size_t)b * NMODC + MOD_SC1 * DM + c), sh = *(const f32x4*)(mods + (size_t)b * NMODC + MOD_SH1 * DM + c);
;             const f32x4 h = (v[j] * rstd) * g * (sc + 1.0f) + sh;
;             u32x2 w; w.x = pg8::cvt_pk_bf16(h[0], h[1]); w.y = pg8::cvt_pk_bf16(h[2], h[3]); o8[64 * j] = w; }
	v_add_f32_e32 v176, v176, v177
	v_fmamk_f32 v176, v176, 0x3a800000, v204
	v_mul_f32_e32 v179, 0x4f800000, v176
	v_cmp_gt_f32_e32 vcc, s20, v176
	s_nop 1
	v_cndmask_b32_e32 v176, v176, v179, vcc
	v_sqrt_f32_e32 v179, v176
	s_nop 0
	v_add_u32_e32 v180, -1, v179
	v_add_u32_e32 v181, 1, v179
	v_fma_f32 v182, -v180, v179, v176
	v_fma_f32 v183, -v181, v179, v176
	v_cmp_ge_f32_e64 s[0:1], 0, v182
	s_nop 1
	v_cndmask_b32_e64 v179, v179, v180, s[0:1]
	v_cmp_lt_f32_e64 s[0:1], 0, v183
	s_nop 1
	v_cndmask_b32_e64 v179, v179, v181, s[0:1]
	v_mul_f32_e32 v180, 0x37800000, v179
	v_cndmask_b32_e32 v179, v179, v180, vcc
	v_cmp_class_f32_e32 vcc, v176, v203
	s_nop 1
	v_cndmask_b32_e32 v176, v179, v176, vcc
	v_div_scale_f32 v179, s[0:1], v176, v176, 1.0
	v_rcp_f32_e32 v180, v179
	v_div_scale_f32 v181, vcc, 1.0, v176, 1.0
	v_fma_f32 v182, -v179, v180, 1.0
	v_fmac_f32_e32 v180, v182, v180
	v_mul_f32_e32 v182, v181, v180
	v_fma_f32 v183, -v179, v182, v181
	v_fmac_f32_e32 v182, v183, v180
	v_fma_f32 v179, -v179, v182, v181
	v_div_fmas_f32 v179, v179, v180, v182
	v_div_fixup_f32 v206, v179, v176, 1.0
	v_pk_mul_f32 v[128:129], v[128:129], v[206:207] op_sel_hi:[1,0]
	v_pk_mul_f32 v[130:131], v[130:131], v[206:207] op_sel_hi:[1,0]
	v_pk_mul_f32 v[128:129], v[64:65], v[128:129]
	v_pk_mul_f32 v[130:131], v[66:67], v[130:131]
	v_pk_fma_f32 v[128:129], v[80:81], v[128:129], v[96:97]
	v_pk_fma_f32 v[130:131], v[82:83], v[130:131], v[98:99]
	v_cvt_pk_bf16_f32 v192, v128, v129
	v_cvt_pk_bf16_f32 v193, v130, v131
	global_store_dwordx2 v34, v[192:193], s[16:17]
	v_pk_mul_f32 v[132:133], v[132:133], v[206:207] op_sel_hi:[1,0]
	v_pk_mul_f32 v[134:135], v[134:135], v[206:207] op_sel_hi:[1,0]
	v_pk_mul_f32 v[132:133], v[68:69], v[132:133]
	v_pk_mul_f32 v[134:135], v[70:71], v[134:135]
	v_pk_fma_f32 v[132:133], v[84:85], v[132:133], v[100:101]
	v_pk_fma_f32 v[134:135], v[86:87], v[134:135], v[102:103]
	v_cvt_pk_bf16_f32 v194, v132, v133
	v_cvt_pk_bf16_f32 v195, v134, v135
	global_store_dwordx2 v34, v[194:195], s[16:17] offset:512
	v_pk_mul_f32 v[136:137], v[136:137], v[206:207] op_sel_hi:[1,0]
	v_pk_mul_f32 v[138:139], v[138:139], v[206:207] op_sel_hi:[1,0]
	v_pk_mul_f32 v[136:137], v[72:73], v[136:137]
	v_pk_mul_f32 v[138:139], v[74:75], v[138:139]
	v_pk_fma_f32 v[136:137], v[88:89], v[136:137], v[104:105]
	v_pk_fma_f32 v[138:139], v[90:91], v[138:139], v[106:107]
	v_cvt_pk_bf16_f32 v196, v136, v137
	v_cvt_pk_bf16_f32 v197, v138, v139
	global_store_dwordx2 v34, v[196:197], s[16:17] offset:1024
	v_pk_mul_f32 v[140:141], v[140:141], v[206:207] op_sel_hi:[1,0]
	v_pk_mul_f32 v[142:143], v[142:143], v[206:207] op_sel_hi:[1,0]
	v_pk_mul_f32 v[140:141], v[76:77], v[140:141]
	v_pk_mul_f32 v[142:143], v[78:79], v[142:143]
	v_pk_fma_f32 v[140:141], v[92:93], v[140:141], v[108:109]
	v_pk_fma_f32 v[142:143], v[94:95], v[142:143], v[110:111]
	v_cvt_pk_bf16_f32 v198, v140, v141
	v_cvt_pk_bf16_f32 v199, v142, v143
	global_store_dwordx2 v34, v[198:199], s[16:17] offset:1536
	s_add_u32 s16, s16, 0x800
	s_addc_u32 s17, s17, 0
	global_load_dwordx4 v[128:131], v200, s[14:15]
	global_load_dwordx4 v[132:135], v200, s[14:15] offset:1024
	global_load_dwordx4 v[136:139], v200, s[14:15] offset:2048
	global_load_dwordx4 v[140:143], v200, s[14:15] offset:3072
	s_add_u32 s14, s14, 0x1000
	s_addc_u32 s15, s15, 0
	s_waitcnt vmcnt(24)
	v_mul_f32_e32 v177, v144, v144
	v_mul_f32_e32 v178, v146, v146
	v_fmac_f32_e32 v177, v145, v145
	v_fmac_f32_e32 v178, v147, v147
	v_add_f32_e32 v176, v177, v178
	v_mul_f32_e32 v177, v148, v148
	v_mul_f32_e32 v178, v150, v150
	v_fmac_f32_e32 v177, v149, v149
	v_fmac_f32_e32 v178, v151, v151
	v_add_f32_e32 v177, v177, v178
	v_add_f32_e32 v176, v176, v177
	v_mul_f32_e32 v177, v152, v152
	v_mul_f32_e32 v178, v154, v154
	v_fmac_f32_e32 v177, v153, v153
	v_fmac_f32_e32 v178, v155, v155
	v_add_f32_e32 v177, v177, v178
	v_add_f32_e32 v176, v176, v177
	v_mul_f32_e32 v177, v156, v156
	v_mul_f32_e32 v178, v158, v158
	v_fmac_f32_e32 v177, v157, v157
	v_fmac_f32_e32 v178, v159, v159
	v_add_f32_e32 v177, v177, v178
	v_add_f32_e32 v176, v176, v177
	s_nop 1
	v_add_f32_dpp v176, v176, v176 quad_perm:[1,0,3,2] row_mask:0xf bank_mask:0xf
	s_nop 1
	v_add_f32_dpp v176, v176, v176 quad_perm:[2,3,0,1] row_mask:0xf bank_mask:0xf
	s_nop 1
	v_add_f32_dpp v176, v176, v176 row_half_mirror row_mask:0xf bank_mask:0xf
	s_nop 1
	v_add_f32_dpp v176, v176, v176 row_mirror row_mask:0xf bank_mask:0xf
	ds_bpermute_b32 v177, v201, v176
	s_waitcnt lgkmcnt(0)
	v_add_f32_e32 v176, v176, v177
	ds_bpermute_b32 v177, v202, v176
	s_waitcnt lgkmcnt(0)
; __device__ __forceinline__ unsigned cvt_pk_bf16(float lo, float hi) { unsigned r; asm volatile("v_cvt_pk_bf16_f32 %0, %1, %2" : "=v"(r) : "v"(lo), "v"(hi)); return r; }
; __device__ __forceinline__ void p1_rows(const Args& A, int lane, int wave) {
;     ...
;         for (int j = 0; j < 4; ++j) s += (v[j][0] * v[j][0] + v[j][1] * v[j][1]) + (v[j][2] * v[j][2] + v[j][3] * v[j][3]);
;         const float rstd = 1.0f / sqrtf(wave_sum(s) * (1.0f / DM) + RMS_EPS);
;         u32x2* o8 = (u32x2*)(HB + (size_t)m * DM) + lane;
; #pragma unroll
;         for (int j = 0; j < 4; ++j) { const int c = 4 * lane + 256 * j;
;             const f32x4 g = *(const f32x4*)(A.g_ffn1 + c), sc = *(const f32x4*)(mods + (size_t)b * NMODC + MOD_SC1 * DM + c), sh = *(const f32x4*)(mods + (size_t)b * NMODC + MOD_SH1 * DM + c);
;             const f32x4 h = (v[j] * rstd) * g * (sc + 1.0f) + sh;
;             u32x2 w; w.x = pg8::cvt_pk_bf16(h[0], h[1]); w.y = pg8::cvt_pk_bf16(h[2], h[3]); o8[64 * j] = w; }
	v_add_f32_e32 v176, v176, v177
	v_fmamk_f32 v176, v176, 0x3a800000, v204
	v_mul_f32_e32 v179, 0x4f800000, v176
	v_cmp_gt_f32_e32 vcc, s20, v176
	s_nop 1
	v_cndmask_b32_e32 v176, v176, v179, vcc
	v_sqrt_f32_e32 v179, v176
	s_nop 0
	v_add_u32_e32 v180, -1, v179
	v_add_u32_e32 v181, 1, v179
	v_fma_f32 v182, -v180, v179, v176
	v_fma_f32 v183, -v181, v179, v176
	v_cmp_ge_f32_e64 s[0:1], 0, v182
	s_nop 1
	v_cndmask_b32_e64 v179, v179, v180, s[0:1]
	v_cmp_lt_f32_e64 s[0:1], 0, v183
	s_nop 1
	v_cndmask_b32_e64 v179, v179, v181, s[0:1]
	v_mul_f32_e32 v180, 0x37800000, v179
	v_cndmask_b32_e32 v179, v179, v180, vcc
	v_cmp_class_f32_e32 vcc, v176, v203
	s_nop 1
	v_cndmask_b32_e32 v176, v179, v176, vcc
	v_div_scale_f32 v179, s[0:1], v176, v176, 1.0
	v_rcp_f32_e32 v180, v179
	v_div_scale_f32 v181, vcc, 1.0, v176, 1.0
	v_fma_f32 v182, -v179, v180, 1.0
	v_fmac_f32_e32 v180, v182, v180
	v_mul_f32_e32 v182, v181, v180
	v_fma_f32 v183, -v179, v182, v181
	v_fmac_f32_e32 v182, v183, v180
	v_fma_f32 v179, -v179, v182, v181
	v_div_fmas_f32 v179, v179, v180, v182
	v_div_fixup_f32 v206, v179, v176, 1.0
	v_pk_mul_f32 v[144:145], v[144:145], v[206:207] op_sel_hi:[1,0]
	v_pk_mul_f32 v[146:147], v[146:147], v[206:207] op_sel_hi:[1,0]
	v_pk_mul_f32 v[144:145], v[64:65], v[144:145]
	v_pk_mul_f32 v[146:147], v[66:67], v[146:147]
	v_pk_fma_f32 v[144:145], v[80:81], v[144:145], v[96:97]
	v_pk_fma_f32 v[146:147], v[82:83], v[146:147], v[98:99]
	v_cvt_pk_bf16_f32 v184, v144, v145
	v_cvt_pk_bf16_f32 v185, v146, v147
	global_store_dwordx2 v34, v[184:185], s[16:17]
	v_pk_mul_f32 v[148:149], v[148:149], v[206:207] op_sel_hi:[1,0]
	v_pk_mul_f32 v[150:151], v[150:151], v[206:207] op_sel_hi:[1,0]
	v_pk_mul_f32 v[148:149], v[68:69], v[148:149]
	v_pk_mul_f32 v[150:151], v[70:71], v[150:151]
	v_pk_fma_f32 v[148:149], v[84:85], v[148:149], v[100:101]
	v_pk_fma_f32 v[150:151], v[86:87], v[150:151], v[102:103]
	v_cvt_pk_bf16_f32 v186, v148, v149
	v_cvt_pk_bf16_f32 v187, v150, v151
	global_store_dwordx2 v34, v[186:187], s[16:17] offset:512
	v_pk_mul_f32 v[152:153], v[152:153], v[206:207] op_sel_hi:[1,0]
	v_pk_mul_f32 v[154:155], v[154:155], v[206:207] op_sel_hi:[1,0]
	v_pk_mul_f32 v[152:153], v[72:73], v[152:153]
	v_pk_mul_f32 v[154:155], v[74:75], v[154:155]
	v_pk_fma_f32 v[152:153], v[88:89], v[152:153], v[104:105]
	v_pk_fma_f32 v[154:155], v[90:91], v[154:155], v[106:107]
	v_cvt_pk_bf16_f32 v188, v152, v153
	v_cvt_pk_bf16_f32 v189, v154, v155
	global_store_dwordx2 v34, v[188:189], s[16:17] offset:1024
	v_pk_mul_f32 v[156:157], v[156:157], v[206:207] op_sel_hi:[1,0]
	v_pk_mul_f32 v[158:159], v[158:159], v[206:207] op_sel_hi:[1,0]
	v_pk_mul_f32 v[156:157], v[76:77], v[156:157]
	v_pk_mul_f32 v[158:159], v[78:79], v[158:159]
	v_pk_fma_f32 v[156:157], v[92:93], v[156:157], v[108:109]
	v_pk_fma_f32 v[158:159], v[94:95], v[158:159], v[110:111]
	v_cvt_pk_bf16_f32 v190, v156, v157
	v_cvt_pk_bf16_f32 v191, v158, v159
	global_store_dwordx2 v34, v[190:191], s[16:17] offset:1536
	s_add_u32 s16, s16, 0x800
	s_addc_u32 s17, s17, 0
	global_load_dwordx4 v[144:147], v200, s[14:15]
	global_load_dwordx4 v[148:151], v200, s[14:15] offset:1024
	global_load_dwordx4 v[152:155], v200, s[14:15] offset:2048
	global_load_dwordx4 v[156:159], v200, s[14:15] offset:3072
	s_add_u32 s14, s14, 0x1000
	s_addc_u32 s15, s15, 0
	s_waitcnt vmcnt(24)
	v_mul_f32_e32 v177, v160, v160
	v_mul_f32_e32 v178, v162, v162
	v_fmac_f32_e32 v177, v161, v161
	v_fmac_f32_e32 v178, v163, v163
	v_add_f32_e32 v176, v177, v178
	v_mul_f32_e32 v177, v164, v164
	v_mul_f32_e32 v178, v166, v166
	v_fmac_f32_e32 v177, v165, v165
	v_fmac_f32_e32 v178, v167, v167
	v_add_f32_e32 v177, v177, v178
	v_add_f32_e32 v176, v176, v177
	v_mul_f32_e32 v177, v168, v168
	v_mul_f32_e32 v178, v170, v170
	v_fmac_f32_e32 v177, v169, v169
	v_fmac_f32_e32 v178, v171, v171
	v_add_f32_e32 v177, v177, v178
	v_add_f32_e32 v176, v176, v177
	v_mul_f32_e32 v177, v172, v172
	v_mul_f32_e32 v178, v174, v174
	v_fmac_f32_e32 v177, v173, v173
	v_fmac_f32_e32 v178, v175, v175
	v_add_f32_e32 v177, v177, v178
	v_add_f32_e32 v176, v176, v177
	s_nop 1
	v_add_f32_dpp v176, v176, v176 quad_perm:[1,0,3,2] row_mask:0xf bank_mask:0xf
	s_nop 1
	v_add_f32_dpp v176, v176, v176 quad_perm:[2,3,0,1] row_mask:0xf bank_mask:0xf
	s_nop 1
	v_add_f32_dpp v176, v176, v176 row_half_mirror row_mask:0xf bank_mask:0xf
	s_nop 1
	v_add_f32_dpp v176, v176, v176 row_mirror row_mask:0xf bank_mask:0xf
	ds_bpermute_b32 v177, v201, v176
	s_waitcnt lgkmcnt(0)
	v_add_f32_e32 v176, v176, v177
	ds_bpermute_b32 v177, v202, v176
	s_waitcnt lgkmcnt(0)
; __device__ __forceinline__ unsigned cvt_pk_bf16(float lo, float hi) { unsigned r; asm volatile("v_cvt_pk_bf16_f32 %0, %1, %2" : "=v"(r) : "v"(lo), "v"(hi)); return r; }
; __device__ __forceinline__ void p1_rows(const Args& A, int lane, int wave) {
;     ...
;         for (int j = 0; j < 4; ++j) s += (v[j][0] * v[j][0] + v[j][1] * v[j][1]) + (v[j][2] * v[j][2] + v[j][3] * v[j][3]);
;         const float rstd = 1.0f / sqrtf(wave_sum(s) * (1.0f / DM) + RMS_EPS);
;         u32x2* o8 = (u32x2*)(HB + (size_t)m * DM) + lane;
; #pragma unroll
;         for (int j = 0; j < 4; ++j) { const int c = 4 * lane + 256 * j;
;             const f32x4 g = *(const f32x4*)(A.g_ffn1 + c), sc = *(const f32x4*)(mods + (size_t)b * NMODC + MOD_SC1 * DM + c), sh = *(const f32x4*)(mods + (size_t)b * NMODC + MOD_SH1 * DM + c);
;             const f32x4 h = (v[j] * rstd) * g * (sc + 1.0f) + sh;
;             u32x2 w; w.x = pg8::cvt_pk_bf16(h[0], h[1]); w.y = pg8::cvt_pk_bf16(h[2], h[3]); o8[64 * j] = w; }
	v_add_f32_e32 v176, v176, v177
	v_fmamk_f32 v176, v176, 0x3a800000, v204
	v_mul_f32_e32 v179, 0x4f800000, v176
	v_cmp_gt_f32_e32 vcc, s20, v176
	s_nop 1
	v_cndmask_b32_e32 v176, v176, v179, vcc
	v_sqrt_f32_e32 v179, v176
	s_nop 0
	v_add_u32_e32 v180, -1, v179
	v_add_u32_e32 v181, 1, v179
	v_fma_f32 v182, -v180, v179, v176
	v_fma_f32 v183, -v181, v179, v176
	v_cmp_ge_f32_e64 s[0:1], 0, v182
	s_nop 1
	v_cndmask_b32_e64 v179, v179, v180, s[0:1]
	v_cmp_lt_f32_e64 s[0:1], 0, v183
	s_nop 1
	v_cndmask_b32_e64 v179, v179, v181, s[0:1]
	v_mul_f32_e32 v180, 0x37800000, v179
	v_cndmask_b32_e32 v179, v179, v180, vcc
	v_cmp_class_f32_e32 vcc, v176, v203
	s_nop 1
	v_cndmask_b32_e32 v176, v179, v176, vcc
	v_div_scale_f32 v179, s[0:1], v176, v176, 1.0
	v_rcp_f32_e32 v180, v179
	v_div_scale_f32 v181, vcc, 1.0, v176, 1.0
	v_fma_f32 v182, -v179, v180, 1.0
	v_fmac_f32_e32 v180, v182, v180
	v_mul_f32_e32 v182, v181, v180
	v_fma_f32 v183, -v179, v182, v181
	v_fmac_f32_e32 v182, v183, v180
	v_fma_f32 v179, -v179, v182, v181
	v_div_fmas_f32 v179, v179, v180, v182
	v_div_fixup_f32 v206, v179, v176, 1.0
	v_pk_mul_f32 v[160:161], v[160:161], v[206:207] op_sel_hi:[1,0]
	v_pk_mul_f32 v[162:163], v[162:163], v[206:207] op_sel_hi:[1,0]
	v_pk_mul_f32 v[160:161], v[64:65], v[160:161]
	v_pk_mul_f32 v[162:163], v[66:67], v[162:163]
	v_pk_fma_f32 v[160:161], v[80:81], v[160:161], v[96:97]
	v_pk_fma_f32 v[162:163], v[82:83], v[162:163], v[98:99]
	v_cvt_pk_bf16_f32 v192, v160, v161
	v_cvt_pk_bf16_f32 v193, v162, v163
	global_store_dwordx2 v34, v[192:193], s[16:17]
	v_pk_mul_f32 v[164:165], v[164:165], v[206:207] op_sel_hi:[1,0]
	v_pk_mul_f32 v[166:167], v[166:167], v[206:207] op_sel_hi:[1,0]
	v_pk_mul_f32 v[164:165], v[68:69], v[164:165]
	v_pk_mul_f32 v[166:167], v[70:71], v[166:167]
	v_pk_fma_f32 v[164:165], v[84:85], v[164:165], v[100:101]
	v_pk_fma_f32 v[166:167], v[86:87], v[166:167], v[102:103]
	v_cvt_pk_bf16_f32 v194, v164, v165
	v_cvt_pk_bf16_f32 v195, v166, v167
	global_store_dwordx2 v34, v[194:195], s[16:17] offset:512
	v_pk_mul_f32 v[168:169], v[168:169], v[206:207] op_sel_hi:[1,0]
	v_pk_mul_f32 v[170:171], v[170:171], v[206:207] op_sel_hi:[1,0]
	v_pk_mul_f32 v[168:169], v[72:73], v[168:169]
	v_pk_mul_f32 v[170:171], v[74:75], v[170:171]
	v_pk_fma_f32 v[168:169], v[88:89], v[168:169], v[104:105]
	v_pk_fma_f32 v[170:171], v[90:91], v[170:171], v[106:107]
	v_cvt_pk_bf16_f32 v196, v168, v169
	v_cvt_pk_bf16_f32 v197, v170, v171
	global_store_dwordx2 v34, v[196:197], s[16:17] offset:1024
	v_pk_mul_f32 v[172:173], v[172:173], v[206:207] op_sel_hi:[1,0]
	v_pk_mul_f32 v[174:175], v[174:175], v[206:207] op_sel_hi:[1,0]
	v_pk_mul_f32 v[172:173], v[76:77], v[172:173]
	v_pk_mul_f32 v[174:175], v[78:79], v[174:175]
	v_pk_fma_f32 v[172:173], v[92:93], v[172:173], v[108:109]
	v_pk_fma_f32 v[174:175], v[94:95], v[174:175], v[110:111]
	v_cvt_pk_bf16_f32 v198, v172, v173
	v_cvt_pk_bf16_f32 v199, v174, v175
	global_store_dwordx2 v34, v[198:199], s[16:17] offset:1536
	s_add_u32 s16, s16, 0x800
	s_addc_u32 s17, s17, 0
	global_load_dwordx4 v[160:163], v200, s[14:15]
	global_load_dwordx4 v[164:167], v200, s[14:15] offset:1024
	global_load_dwordx4 v[168:171], v200, s[14:15] offset:2048
	global_load_dwordx4 v[172:175], v200, s[14:15] offset:3072
	s_add_u32 s14, s14, 0x1000
	s_addc_u32 s15, s15, 0
	s_waitcnt vmcnt(24)
	v_mul_f32_e32 v177, v112, v112
	v_mul_f32_e32 v178, v114, v114
	v_fmac_f32_e32 v177, v113, v113
	v_fmac_f32_e32 v178, v115, v115
	v_add_f32_e32 v176, v177, v178
	v_mul_f32_e32 v177, v116, v116
	v_mul_f32_e32 v178, v118, v118
	v_fmac_f32_e32 v177, v117, v117
	v_fmac_f32_e32 v178, v119, v119
	v_add_f32_e32 v177, v177, v178
	v_add_f32_e32 v176, v176, v177
	v_mul_f32_e32 v177, v120, v120
	v_mul_f32_e32 v178, v122, v122
	v_fmac_f32_e32 v177, v121, v121
	v_fmac_f32_e32 v178, v123, v123
	v_add_f32_e32 v177, v177, v178
	v_add_f32_e32 v176, v176, v177
	v_mul_f32_e32 v177, v124, v124
	v_mul_f32_e32 v178, v126, v126
	v_fmac_f32_e32 v177, v125, v125
	v_fmac_f32_e32 v178, v127, v127
	v_add_f32_e32 v177, v177, v178
	v_add_f32_e32 v176, v176, v177
	s_nop 1
	v_add_f32_dpp v176, v176, v176 quad_perm:[1,0,3,2] row_mask:0xf bank_mask:0xf
	s_nop 1
	v_add_f32_dpp v176, v176, v176 quad_perm:[2,3,0,1] row_mask:0xf bank_mask:0xf
	s_nop 1
	v_add_f32_dpp v176, v176, v176 row_half_mirror row_mask:0xf bank_mask:0xf
	s_nop 1
	v_add_f32_dpp v176, v176, v176 row_mirror row_mask:0xf bank_mask:0xf
	ds_bpermute_b32 v177, v201, v176
	s_waitcnt lgkmcnt(0)
	v_add_f32_e32 v176, v176, v177
	ds_bpermute_b32 v177, v202, v176
	s_waitcnt lgkmcnt(0)
; __device__ __forceinline__ unsigned cvt_pk_bf16(float lo, float hi) { unsigned r; asm volatile("v_cvt_pk_bf16_f32 %0, %1, %2" : "=v"(r) : "v"(lo), "v"(hi)); return r; }
; __device__ __forceinline__ void p1_rows(const Args& A, int lane, int wave) {
;     ...
;         for (int j = 0; j < 4; ++j) s += (v[j][0] * v[j][0] + v[j][1] * v[j][1]) + (v[j][2] * v[j][2] + v[j][3] * v[j][3]);
;         const float rstd = 1.0f / sqrtf(wave_sum(s) * (1.0f / DM) + RMS_EPS);
;         u32x2* o8 = (u32x2*)(HB + (size_t)m * DM) + lane;
; #pragma unroll
;         for (int j = 0; j < 4; ++j) { const int c = 4 * lane + 256 * j;
;             const f32x4 g = *(const f32x4*)(A.g_ffn1 + c), sc = *(const f32x4*)(mods + (size_t)b * NMODC + MOD_SC1 * DM + c), sh = *(const f32x4*)(mods + (size_t)b * NMODC + MOD_SH1 * DM + c);
;             const f32x4 h = (v[j] * rstd) * g * (sc + 1.0f) + sh;
;             u32x2 w; w.x = pg8::cvt_pk_bf16(h[0], h[1]); w.y = pg8::cvt_pk_bf16(h[2], h[3]); o8[64 * j] = w; }
	v_add_f32_e32 v176, v176, v177
	v_fmamk_f32 v176, v176, 0x3a800000, v204
	v_mul_f32_e32 v179, 0x4f800000, v176
	v_cmp_gt_f32_e32 vcc, s20, v176
	s_nop 1
	v_cndmask_b32_e32 v176, v176, v179, vcc
	v_sqrt_f32_e32 v179, v176
	s_nop 0
	v_add_u32_e32 v180, -1, v179
	v_add_u32_e32 v181, 1, v179
	v_fma_f32 v182, -v180, v179, v176
	v_fma_f32 v183, -v181, v179, v176
	v_cmp_ge_f32_e64 s[0:1], 0, v182
	s_nop 1
	v_cndmask_b32_e64 v179, v179, v180, s[0:1]
	v_cmp_lt_f32_e64 s[0:1], 0, v183
	s_nop 1
	v_cndmask_b32_e64 v179, v179, v181, s[0:1]
	v_mul_f32_e32 v180, 0x37800000, v179
	v_cndmask_b32_e32 v179, v179, v180, vcc
	v_cmp_class_f32_e32 vcc, v176, v203
	s_nop 1
	v_cndmask_b32_e32 v176, v179, v176, vcc
	v_div_scale_f32 v179, s[0:1], v176, v176, 1.0
	v_rcp_f32_e32 v180, v179
	v_div_scale_f32 v181, vcc, 1.0, v176, 1.0
	v_fma_f32 v182, -v179, v180, 1.0
	v_fmac_f32_e32 v180, v182, v180
	v_mul_f32_e32 v182, v181, v180
	v_fma_f32 v183, -v179, v182, v181
	v_fmac_f32_e32 v182, v183, v180
	v_fma_f32 v179, -v179, v182, v181
	v_div_fmas_f32 v179, v179, v180, v182
	v_div_fixup_f32 v206, v179, v176, 1.0
	v_pk_mul_f32 v[112:113], v[112:113], v[206:207] op_sel_hi:[1,0]
	v_pk_mul_f32 v[114:115], v[114:115], v[206:207] op_sel_hi:[1,0]
	v_pk_mul_f32 v[112:113], v[64:65], v[112:113]
	v_pk_mul_f32 v[114:115], v[66:67], v[114:115]
	v_pk_fma_f32 v[112:113], v[80:81], v[112:113], v[96:97]
	v_pk_fma_f32 v[114:115], v[82:83], v[114:115], v[98:99]
	v_cvt_pk_bf16_f32 v184, v112, v113
	v_cvt_pk_bf16_f32 v185, v114, v115
	global_store_dwordx2 v34, v[184:185], s[16:17]
	v_pk_mul_f32 v[116:117], v[116:117], v[206:207] op_sel_hi:[1,0]
	v_pk_mul_f32 v[118:119], v[118:119], v[206:207] op_sel_hi:[1,0]
	v_pk_mul_f32 v[116:117], v[68:69], v[116:117]
	v_pk_mul_f32 v[118:119], v[70:71], v[118:119]
	v_pk_fma_f32 v[116:117], v[84:85], v[116:117], v[100:101]
	v_pk_fma_f32 v[118:119], v[86:87], v[118:119], v[102:103]
	v_cvt_pk_bf16_f32 v186, v116, v117
	v_cvt_pk_bf16_f32 v187, v118, v119
	global_store_dwordx2 v34, v[186:187], s[16:17] offset:512
	v_pk_mul_f32 v[120:121], v[120:121], v[206:207] op_sel_hi:[1,0]
	v_pk_mul_f32 v[122:123], v[122:123], v[206:207] op_sel_hi:[1,0]
	v_pk_mul_f32 v[120:121], v[72:73], v[120:121]
	v_pk_mul_f32 v[122:123], v[74:75], v[122:123]
	v_pk_fma_f32 v[120:121], v[88:89], v[120:121], v[104:105]
	v_pk_fma_f32 v[122:123], v[90:91], v[122:123], v[106:107]
	v_cvt_pk_bf16_f32 v188, v120, v121
	v_cvt_pk_bf16_f32 v189, v122, v123
	global_store_dwordx2 v34, v[188:189], s[16:17] offset:1024
	v_pk_mul_f32 v[124:125], v[124:125], v[206:207] op_sel_hi:[1,0]
	v_pk_mul_f32 v[126:127], v[126:127], v[206:207] op_sel_hi:[1,0]
	v_pk_mul_f32 v[124:125], v[76:77], v[124:125]
	v_pk_mul_f32 v[126:127], v[78:79], v[126:127]
	v_pk_fma_f32 v[124:125], v[92:93], v[124:125], v[108:109]
	v_pk_fma_f32 v[126:127], v[94:95], v[126:127], v[110:111]
	v_cvt_pk_bf16_f32 v190, v124, v125
	v_cvt_pk_bf16_f32 v191, v126, v127
	global_store_dwordx2 v34, v[190:191], s[16:17] offset:1536
	s_add_u32 s16, s16, 0x800
	s_addc_u32 s17, s17, 0
	global_load_dwordx4 v[112:115], v200, s[14:15]
	global_load_dwordx4 v[116:119], v200, s[14:15] offset:1024
	global_load_dwordx4 v[120:123], v200, s[14:15] offset:2048
	global_load_dwordx4 v[124:127], v200, s[14:15] offset:3072
	s_add_u32 s14, s14, 0x1000
	s_addc_u32 s15, s15, 0
	s_waitcnt vmcnt(24)
	v_mul_f32_e32 v177, v128, v128
	v_mul_f32_e32 v178, v130, v130
	v_fmac_f32_e32 v177, v129, v129
	v_fmac_f32_e32 v178, v131, v131
	v_add_f32_e32 v176, v177, v178
	v_mul_f32_e32 v177, v132, v132
	v_mul_f32_e32 v178, v134, v134
	v_fmac_f32_e32 v177, v133, v133
	v_fmac_f32_e32 v178, v135, v135
	v_add_f32_e32 v177, v177, v178
	v_add_f32_e32 v176, v176, v177
	v_mul_f32_e32 v177, v136, v136
	v_mul_f32_e32 v178, v138, v138
	v_fmac_f32_e32 v177, v137, v137
	v_fmac_f32_e32 v178, v139, v139
	v_add_f32_e32 v177, v177, v178
	v_add_f32_e32 v176, v176, v177
	v_mul_f32_e32 v177, v140, v140
	v_mul_f32_e32 v178, v142, v142
	v_fmac_f32_e32 v177, v141, v141
	v_fmac_f32_e32 v178, v143, v143
	v_add_f32_e32 v177, v177, v178
	v_add_f32_e32 v176, v176, v177
	s_nop 1
	v_add_f32_dpp v176, v176, v176 quad_perm:[1,0,3,2] row_mask:0xf bank_mask:0xf
	s_nop 1
	v_add_f32_dpp v176, v176, v176 quad_perm:[2,3,0,1] row_mask:0xf bank_mask:0xf
	s_nop 1
	v_add_f32_dpp v176, v176, v176 row_half_mirror row_mask:0xf bank_mask:0xf
	s_nop 1
	v_add_f32_dpp v176, v176, v176 row_mirror row_mask:0xf bank_mask:0xf
	ds_bpermute_b32 v177, v201, v176
	s_waitcnt lgkmcnt(0)
	v_add_f32_e32 v176, v176, v177
	ds_bpermute_b32 v177, v202, v176
	s_waitcnt lgkmcnt(0)
; __device__ __forceinline__ unsigned cvt_pk_bf16(float lo, float hi) { unsigned r; asm volatile("v_cvt_pk_bf16_f32 %0, %1, %2" : "=v"(r) : "v"(lo), "v"(hi)); return r; }
; __device__ __forceinline__ void p1_rows(const Args& A, int lane, int wave) {
;     ...
;         for (int j = 0; j < 4; ++j) s += (v[j][0] * v[j][0] + v[j][1] * v[j][1]) + (v[j][2] * v[j][2] + v[j][3] * v[j][3]);
;         const float rstd = 1.0f / sqrtf(wave_sum(s) * (1.0f / DM) + RMS_EPS);
;         u32x2* o8 = (u32x2*)(HB + (size_t)m * DM) + lane;
; #pragma unroll
;         for (int j = 0; j < 4; ++j) { const int c = 4 * lane + 256 * j;
;             const f32x4 g = *(const f32x4*)(A.g_ffn1 + c), sc = *(const f32x4*)(mods + (size_t)b * NMODC + MOD_SC1 * DM + c), sh = *(const f32x4*)(mods + (size_t)b * NMODC + MOD_SH1 * DM + c);
;             const f32x4 h = (v[j] * rstd) * g * (sc + 1.0f) + sh;
;             u32x2 w; w.x = pg8::cvt_pk_bf16(h[0], h[1]); w.y = pg8::cvt_pk_bf16(h[2], h[3]); o8[64 * j] = w; }
	v_add_f32_e32 v176, v176, v177
	v_fmamk_f32 v176, v176, 0x3a800000, v204
	v_mul_f32_e32 v179, 0x4f800000, v176
	v_cmp_gt_f32_e32 vcc, s20, v176
	s_nop 1
	v_cndmask_b32_e32 v176, v176, v179, vcc
	v_sqrt_f32_e32 v179, v176
	s_nop 0
	v_add_u32_e32 v180, -1, v179
	v_add_u32_e32 v181, 1, v179
	v_fma_f32 v182, -v180, v179, v176
	v_fma_f32 v183, -v181, v179, v176
	v_cmp_ge_f32_e64 s[0:1], 0, v182
	s_nop 1
	v_cndmask_b32_e64 v179, v179, v180, s[0:1]
	v_cmp_lt_f32_e64 s[0:1], 0, v183
	s_nop 1
	v_cndmask_b32_e64 v179, v179, v181, s[0:1]
	v_mul_f32_e32 v180, 0x37800000, v179
	v_cndmask_b32_e32 v179, v179, v180, vcc
	v_cmp_class_f32_e32 vcc, v176, v203
	s_nop 1
	v_cndmask_b32_e32 v176, v179, v176, vcc
	v_div_scale_f32 v179, s[0:1], v176, v176, 1.0
	v_rcp_f32_e32 v180, v179
	v_div_scale_f32 v181, vcc, 1.0, v176, 1.0
	v_fma_f32 v182, -v179, v180, 1.0
	v_fmac_f32_e32 v180, v182, v180
	v_mul_f32_e32 v182, v181, v180
	v_fma_f32 v183, -v179, v182, v181
	v_fmac_f32_e32 v182, v183, v180
	v_fma_f32 v179, -v179, v182, v181
	v_div_fmas_f32 v179, v179, v180, v182
	v_div_fixup_f32 v206, v179, v176, 1.0
	v_pk_mul_f32 v[128:129], v[128:129], v[206:207] op_sel_hi:[1,0]
	v_pk_mul_f32 v[130:131], v[130:131], v[206:207] op_sel_hi:[1,0]
	v_pk_mul_f32 v[128:129], v[64:65], v[128:129]
	v_pk_mul_f32 v[130:131], v[66:67], v[130:131]
	v_pk_fma_f32 v[128:129], v[80:81], v[128:129], v[96:97]
	v_pk_fma_f32 v[130:131], v[82:83], v[130:131], v[98:99]
	v_cvt_pk_bf16_f32 v192, v128, v129
	v_cvt_pk_bf16_f32 v193, v130, v131
	global_store_dwordx2 v34, v[192:193], s[16:17]
	v_pk_mul_f32 v[132:133], v[132:133], v[206:207] op_sel_hi:[1,0]
	v_pk_mul_f32 v[134:135], v[134:135], v[206:207] op_sel_hi:[1,0]
	v_pk_mul_f32 v[132:133], v[68:69], v[132:133]
	v_pk_mul_f32 v[134:135], v[70:71], v[134:135]
	v_pk_fma_f32 v[132:133], v[84:85], v[132:133], v[100:101]
	v_pk_fma_f32 v[134:135], v[86:87], v[134:135], v[102:103]
	v_cvt_pk_bf16_f32 v194, v132, v133
	v_cvt_pk_bf16_f32 v195, v134, v135
	global_store_dwordx2 v34, v[194:195], s[16:17] offset:512
	v_pk_mul_f32 v[136:137], v[136:137], v[206:207] op_sel_hi:[1,0]
	v_pk_mul_f32 v[138:139], v[138:139], v[206:207] op_sel_hi:[1,0]
	v_pk_mul_f32 v[136:137], v[72:73], v[136:137]
	v_pk_mul_f32 v[138:139], v[74:75], v[138:139]
	v_pk_fma_f32 v[136:137], v[88:89], v[136:137], v[104:105]
	v_pk_fma_f32 v[138:139], v[90:91], v[138:139], v[106:107]
	v_cvt_pk_bf16_f32 v196, v136, v137
	v_cvt_pk_bf16_f32 v197, v138, v139
	global_store_dwordx2 v34, v[196:197], s[16:17] offset:1024
	v_pk_mul_f32 v[140:141], v[140:141], v[206:207] op_sel_hi:[1,0]
	v_pk_mul_f32 v[142:143], v[142:143], v[206:207] op_sel_hi:[1,0]
	v_pk_mul_f32 v[140:141], v[76:77], v[140:141]
	v_pk_mul_f32 v[142:143], v[78:79], v[142:143]
	v_pk_fma_f32 v[140:141], v[92:93], v[140:141], v[108:109]
	v_pk_fma_f32 v[142:143], v[94:95], v[142:143], v[110:111]
	v_cvt_pk_bf16_f32 v198, v140, v141
	v_cvt_pk_bf16_f32 v199, v142, v143
	global_store_dwordx2 v34, v[198:199], s[16:17] offset:1536
	s_add_u32 s16, s16, 0x800
	s_addc_u32 s17, s17, 0
	global_load_dwordx4 v[128:131], v200, s[14:15]
	global_load_dwordx4 v[132:135], v200, s[14:15] offset:1024
	global_load_dwordx4 v[136:139], v200, s[14:15] offset:2048
	global_load_dwordx4 v[140:143], v200, s[14:15] offset:3072
	s_add_u32 s14, s14, 0x1000
	s_addc_u32 s15, s15, 0
	s_waitcnt vmcnt(24)
	v_mul_f32_e32 v177, v144, v144
	v_mul_f32_e32 v178, v146, v146
	v_fmac_f32_e32 v177, v145, v145
	v_fmac_f32_e32 v178, v147, v147
	v_add_f32_e32 v176, v177, v178
	v_mul_f32_e32 v177, v148, v148
	v_mul_f32_e32 v178, v150, v150
	v_fmac_f32_e32 v177, v149, v149
	v_fmac_f32_e32 v178, v151, v151
	v_add_f32_e32 v177, v177, v178
	v_add_f32_e32 v176, v176, v177
	v_mul_f32_e32 v177, v152, v152
	v_mul_f32_e32 v178, v154, v154
	v_fmac_f32_e32 v177, v153, v153
	v_fmac_f32_e32 v178, v155, v155
	v_add_f32_e32 v177, v177, v178
	v_add_f32_e32 v176, v176, v177
	v_mul_f32_e32 v177, v156, v156
	v_mul_f32_e32 v178, v158, v158
	v_fmac_f32_e32 v177, v157, v157
	v_fmac_f32_e32 v178, v159, v159
	v_add_f32_e32 v177, v177, v178
	v_add_f32_e32 v176, v176, v177
	s_nop 1
	v_add_f32_dpp v176, v176, v176 quad_perm:[1,0,3,2] row_mask:0xf bank_mask:0xf
	s_nop 1
	v_add_f32_dpp v176, v176, v176 quad_perm:[2,3,0,1] row_mask:0xf bank_mask:0xf
	s_nop 1
	v_add_f32_dpp v176, v176, v176 row_half_mirror row_mask:0xf bank_mask:0xf
	s_nop 1
	v_add_f32_dpp v176, v176, v176 row_mirror row_mask:0xf bank_mask:0xf
	ds_bpermute_b32 v177, v201, v176
	s_waitcnt lgkmcnt(0)
	v_add_f32_e32 v176, v176, v177
	ds_bpermute_b32 v177, v202, v176
	s_waitcnt lgkmcnt(0)
; __device__ __forceinline__ unsigned cvt_pk_bf16(float lo, float hi) { unsigned r; asm volatile("v_cvt_pk_bf16_f32 %0, %1, %2" : "=v"(r) : "v"(lo), "v"(hi)); return r; }
; __device__ __forceinline__ void p1_rows(const Args& A, int lane, int wave) {
;     ...
;         for (int j = 0; j < 4; ++j) s += (v[j][0] * v[j][0] + v[j][1] * v[j][1]) + (v[j][2] * v[j][2] + v[j][3] * v[j][3]);
;         const float rstd = 1.0f / sqrtf(wave_sum(s) * (1.0f / DM) + RMS_EPS);
;         u32x2* o8 = (u32x2*)(HB + (size_t)m * DM) + lane;
; #pragma unroll
;         for (int j = 0; j < 4; ++j) { const int c = 4 * lane + 256 * j;
;             const f32x4 g = *(const f32x4*)(A.g_ffn1 + c), sc = *(const f32x4*)(mods + (size_t)b * NMODC + MOD_SC1 * DM + c), sh = *(const f32x4*)(mods + (size_t)b * NMODC + MOD_SH1 * DM + c);
;             const f32x4 h = (v[j] * rstd) * g * (sc + 1.0f) + sh;
;             u32x2 w; w.x = pg8::cvt_pk_bf16(h[0], h[1]); w.y = pg8::cvt_pk_bf16(h[2], h[3]); o8[64 * j] = w; }
	v_add_f32_e32 v176, v176, v177
	v_fmamk_f32 v176, v176, 0x3a800000, v204
	v_mul_f32_e32 v179, 0x4f800000, v176
	v_cmp_gt_f32_e32 vcc, s20, v176
	s_nop 1
	v_cndmask_b32_e32 v176, v176, v179, vcc
	v_sqrt_f32_e32 v179, v176
	s_nop 0
	v_add_u32_e32 v180, -1, v179
	v_add_u32_e32 v181, 1, v179
	v_fma_f32 v182, -v180, v179, v176
	v_fma_f32 v183, -v181, v179, v176
	v_cmp_ge_f32_e64 s[0:1], 0, v182
	s_nop 1
	v_cndmask_b32_e64 v179, v179, v180, s[0:1]
	v_cmp_lt_f32_e64 s[0:1], 0, v183
	s_nop 1
	v_cndmask_b32_e64 v179, v179, v181, s[0:1]
	v_mul_f32_e32 v180, 0x37800000, v179
	v_cndmask_b32_e32 v179, v179, v180, vcc
	v_cmp_class_f32_e32 vcc, v176, v203
	s_nop 1
	v_cndmask_b32_e32 v176, v179, v176, vcc
	v_div_scale_f32 v179, s[0:1], v176, v176, 1.0
	v_rcp_f32_e32 v180, v179
	v_div_scale_f32 v181, vcc, 1.0, v176, 1.0
	v_fma_f32 v182, -v179, v180, 1.0
	v_fmac_f32_e32 v180, v182, v180
	v_mul_f32_e32 v182, v181, v180
	v_fma_f32 v183, -v179, v182, v181
	v_fmac_f32_e32 v182, v183, v180
	v_fma_f32 v179, -v179, v182, v181
	v_div_fmas_f32 v179, v179, v180, v182
	v_div_fixup_f32 v206, v179, v176, 1.0
	v_pk_mul_f32 v[144:145], v[144:145], v[206:207] op_sel_hi:[1,0]
	v_pk_mul_f32 v[146:147], v[146:147], v[206:207] op_sel_hi:[1,0]
	v_pk_mul_f32 v[144:145], v[64:65], v[144:145]
	v_pk_mul_f32 v[146:147], v[66:67], v[146:147]
	v_pk_fma_f32 v[144:145], v[80:81], v[144:145], v[96:97]
	v_pk_fma_f32 v[146:147], v[82:83], v[146:147], v[98:99]
	v_cvt_pk_bf16_f32 v184, v144, v145
	v_cvt_pk_bf16_f32 v185, v146, v147
	global_store_dwordx2 v34, v[184:185], s[16:17]
	v_pk_mul_f32 v[148:149], v[148:149], v[206:207] op_sel_hi:[1,0]
	v_pk_mul_f32 v[150:151], v[150:151], v[206:207] op_sel_hi:[1,0]
	v_pk_mul_f32 v[148:149], v[68:69], v[148:149]
	v_pk_mul_f32 v[150:151], v[70:71], v[150:151]
	v_pk_fma_f32 v[148:149], v[84:85], v[148:149], v[100:101]
	v_pk_fma_f32 v[150:151], v[86:87], v[150:151], v[102:103]
	v_cvt_pk_bf16_f32 v186, v148, v149
	v_cvt_pk_bf16_f32 v187, v150, v151
	global_store_dwordx2 v34, v[186:187], s[16:17] offset:512
	v_pk_mul_f32 v[152:153], v[152:153], v[206:207] op_sel_hi:[1,0]
	v_pk_mul_f32 v[154:155], v[154:155], v[206:207] op_sel_hi:[1,0]
	v_pk_mul_f32 v[152:153], v[72:73], v[152:153]
	v_pk_mul_f32 v[154:155], v[74:75], v[154:155]
	v_pk_fma_f32 v[152:153], v[88:89], v[152:153], v[104:105]
	v_pk_fma_f32 v[154:155], v[90:91], v[154:155], v[106:107]
	v_cvt_pk_bf16_f32 v188, v152, v153
	v_cvt_pk_bf16_f32 v189, v154, v155
	global_store_dwordx2 v34, v[188:189], s[16:17] offset:1024
	v_pk_mul_f32 v[156:157], v[156:157], v[206:207] op_sel_hi:[1,0]
	v_pk_mul_f32 v[158:159], v[158:159], v[206:207] op_sel_hi:[1,0]
	v_pk_mul_f32 v[156:157], v[76:77], v[156:157]
	v_pk_mul_f32 v[158:159], v[78:79], v[158:159]
	v_pk_fma_f32 v[156:157], v[92:93], v[156:157], v[108:109]
	v_pk_fma_f32 v[158:159], v[94:95], v[158:159], v[110:111]
	v_cvt_pk_bf16_f32 v190, v156, v157
	v_cvt_pk_bf16_f32 v191, v158, v159
	global_store_dwordx2 v34, v[190:191], s[16:17] offset:1536
	s_add_u32 s16, s16, 0x800
	s_addc_u32 s17, s17, 0
	global_load_dwordx4 v[144:147], v200, s[14:15]
	global_load_dwordx4 v[148:151], v200, s[14:15] offset:1024
	global_load_dwordx4 v[152:155], v200, s[14:15] offset:2048
	global_load_dwordx4 v[156:159], v200, s[14:15] offset:3072
	s_add_u32 s14, s14, 0x1000
	s_addc_u32 s15, s15, 0
	s_waitcnt vmcnt(24)
	v_mul_f32_e32 v177, v160, v160
	v_mul_f32_e32 v178, v162, v162
	v_fmac_f32_e32 v177, v161, v161
	v_fmac_f32_e32 v178, v163, v163
	v_add_f32_e32 v176, v177, v178
	v_mul_f32_e32 v177, v164, v164
	v_mul_f32_e32 v178, v166, v166
	v_fmac_f32_e32 v177, v165, v165
	v_fmac_f32_e32 v178, v167, v167
	v_add_f32_e32 v177, v177, v178
	v_add_f32_e32 v176, v176, v177
	v_mul_f32_e32 v177, v168, v168
	v_mul_f32_e32 v178, v170, v170
	v_fmac_f32_e32 v177, v169, v169
	v_fmac_f32_e32 v178, v171, v171
	v_add_f32_e32 v177, v177, v178
	v_add_f32_e32 v176, v176, v177
	v_mul_f32_e32 v177, v172, v172
	v_mul_f32_e32 v178, v174, v174
	v_fmac_f32_e32 v177, v173, v173
	v_fmac_f32_e32 v178, v175, v175
	v_add_f32_e32 v177, v177, v178
	v_add_f32_e32 v176, v176, v177
	s_nop 1
	v_add_f32_dpp v176, v176, v176 quad_perm:[1,0,3,2] row_mask:0xf bank_mask:0xf
	s_nop 1
	v_add_f32_dpp v176, v176, v176 quad_perm:[2,3,0,1] row_mask:0xf bank_mask:0xf
	s_nop 1
	v_add_f32_dpp v176, v176, v176 row_half_mirror row_mask:0xf bank_mask:0xf
	s_nop 1
	v_add_f32_dpp v176, v176, v176 row_mirror row_mask:0xf bank_mask:0xf
	ds_bpermute_b32 v177, v201, v176
	s_waitcnt lgkmcnt(0)
	v_add_f32_e32 v176, v176, v177
	ds_bpermute_b32 v177, v202, v176
	s_waitcnt lgkmcnt(0)
; __device__ __forceinline__ unsigned cvt_pk_bf16(float lo, float hi) { unsigned r; asm volatile("v_cvt_pk_bf16_f32 %0, %1, %2" : "=v"(r) : "v"(lo), "v"(hi)); return r; }
; __device__ __forceinline__ void p1_rows(const Args& A, int lane, int wave) {
;     ...
;         for (int j = 0; j < 4; ++j) s += (v[j][0] * v[j][0] + v[j][1] * v[j][1]) + (v[j][2] * v[j][2] + v[j][3] * v[j][3]);
;         const float rstd = 1.0f / sqrtf(wave_sum(s) * (1.0f / DM) + RMS_EPS);
;         u32x2* o8 = (u32x2*)(HB + (size_t)m * DM) + lane;
; #pragma unroll
;         for (int j = 0; j < 4; ++j) { const int c = 4 * lane + 256 * j;
;             const f32x4 g = *(const f32x4*)(A.g_ffn1 + c), sc = *(const f32x4*)(mods + (size_t)b * NMODC + MOD_SC1 * DM + c), sh = *(const f32x4*)(mods + (size_t)b * NMODC + MOD_SH1 * DM + c);
;             const f32x4 h = (v[j] * rstd) * g * (sc + 1.0f) + sh;
;             u32x2 w; w.x = pg8::cvt_pk_bf16(h[0], h[1]); w.y = pg8::cvt_pk_bf16(h[2], h[3]); o8[64 * j] = w; }
	v_add_f32_e32 v176, v176, v177
	v_fmamk_f32 v176, v176, 0x3a800000, v204
	v_mul_f32_e32 v179, 0x4f800000, v176
	v_cmp_gt_f32_e32 vcc, s20, v176
	s_nop 1
	v_cndmask_b32_e32 v176, v176, v179, vcc
	v_sqrt_f32_e32 v179, v176
	s_nop 0
	v_add_u32_e32 v180, -1, v179
	v_add_u32_e32 v181, 1, v179
	v_fma_f32 v182, -v180, v179, v176
	v_fma_f32 v183, -v181, v179, v176
	v_cmp_ge_f32_e64 s[0:1], 0, v182
	s_nop 1
	v_cndmask_b32_e64 v179, v179, v180, s[0:1]
	v_cmp_lt_f32_e64 s[0:1], 0, v183
	s_nop 1
	v_cndmask_b32_e64 v179, v179, v181, s[0:1]
	v_mul_f32_e32 v180, 0x37800000, v179
	v_cndmask_b32_e32 v179, v179, v180, vcc
	v_cmp_class_f32_e32 vcc, v176, v203
	s_nop 1
	v_cndmask_b32_e32 v176, v179, v176, vcc
	v_div_scale_f32 v179, s[0:1], v176, v176, 1.0
	v_rcp_f32_e32 v180, v179
	v_div_scale_f32 v181, vcc, 1.0, v176, 1.0
	v_fma_f32 v182, -v179, v180, 1.0
	v_fmac_f32_e32 v180, v182, v180
	v_mul_f32_e32 v182, v181, v180
	v_fma_f32 v183, -v179, v182, v181
	v_fmac_f32_e32 v182, v183, v180
	v_fma_f32 v179, -v179, v182, v181
	v_div_fmas_f32 v179, v179, v180, v182
	v_div_fixup_f32 v206, v179, v176, 1.0
	v_pk_mul_f32 v[160:161], v[160:161], v[206:207] op_sel_hi:[1,0]
	v_pk_mul_f32 v[162:163], v[162:163], v[206:207] op_sel_hi:[1,0]
	v_pk_mul_f32 v[160:161], v[64:65], v[160:161]
	v_pk_mul_f32 v[162:163], v[66:67], v[162:163]
	v_pk_fma_f32 v[160:161], v[80:81], v[160:161], v[96:97]
	v_pk_fma_f32 v[162:163], v[82:83], v[162:163], v[98:99]
	v_cvt_pk_bf16_f32 v192, v160, v161
	v_cvt_pk_bf16_f32 v193, v162, v163
	global_store_dwordx2 v34, v[192:193], s[16:17]
	v_pk_mul_f32 v[164:165], v[164:165], v[206:207] op_sel_hi:[1,0]
	v_pk_mul_f32 v[166:167], v[166:167], v[206:207] op_sel_hi:[1,0]
	v_pk_mul_f32 v[164:165], v[68:69], v[164:165]
	v_pk_mul_f32 v[166:167], v[70:71], v[166:167]
	v_pk_fma_f32 v[164:165], v[84:85], v[164:165], v[100:101]
	v_pk_fma_f32 v[166:167], v[86:87], v[166:167], v[102:103]
	v_cvt_pk_bf16_f32 v194, v164, v165
	v_cvt_pk_bf16_f32 v195, v166, v167
	global_store_dwordx2 v34, v[194:195], s[16:17] offset:512
	v_pk_mul_f32 v[168:169], v[168:169], v[206:207] op_sel_hi:[1,0]
	v_pk_mul_f32 v[170:171], v[170:171], v[206:207] op_sel_hi:[1,0]
	v_pk_mul_f32 v[168:169], v[72:73], v[168:169]
	v_pk_mul_f32 v[170:171], v[74:75], v[170:171]
	v_pk_fma_f32 v[168:169], v[88:89], v[168:169], v[104:105]
	v_pk_fma_f32 v[170:171], v[90:91], v[170:171], v[106:107]
	v_cvt_pk_bf16_f32 v196, v168, v169
	v_cvt_pk_bf16_f32 v197, v170, v171
	global_store_dwordx2 v34, v[196:197], s[16:17] offset:1024
	v_pk_mul_f32 v[172:173], v[172:173], v[206:207] op_sel_hi:[1,0]
	v_pk_mul_f32 v[174:175], v[174:175], v[206:207] op_sel_hi:[1,0]
	v_pk_mul_f32 v[172:173], v[76:77], v[172:173]
	v_pk_mul_f32 v[174:175], v[78:79], v[174:175]
	v_pk_fma_f32 v[172:173], v[92:93], v[172:173], v[108:109]
	v_pk_fma_f32 v[174:175], v[94:95], v[174:175], v[110:111]
	v_cvt_pk_bf16_f32 v198, v172, v173
	v_cvt_pk_bf16_f32 v199, v174, v175
	global_store_dwordx2 v34, v[198:199], s[16:17] offset:1536
	s_add_u32 s16, s16, 0x800
	s_addc_u32 s17, s17, 0
	global_load_dwordx4 v[160:163], v200, s[14:15]
	global_load_dwordx4 v[164:167], v200, s[14:15] offset:1024
	global_load_dwordx4 v[168:171], v200, s[14:15] offset:2048
	global_load_dwordx4 v[172:175], v200, s[14:15] offset:3072
	s_add_u32 s14, s14, 0x1000
	s_addc_u32 s15, s15, 0
	s_waitcnt vmcnt(24)
	v_mul_f32_e32 v177, v112, v112
	v_mul_f32_e32 v178, v114, v114
	v_fmac_f32_e32 v177, v113, v113
	v_fmac_f32_e32 v178, v115, v115
	v_add_f32_e32 v176, v177, v178
	v_mul_f32_e32 v177, v116, v116
	v_mul_f32_e32 v178, v118, v118
	v_fmac_f32_e32 v177, v117, v117
	v_fmac_f32_e32 v178, v119, v119
	v_add_f32_e32 v177, v177, v178
	v_add_f32_e32 v176, v176, v177
	v_mul_f32_e32 v177, v120, v120
	v_mul_f32_e32 v178, v122, v122
	v_fmac_f32_e32 v177, v121, v121
	v_fmac_f32_e32 v178, v123, v123
	v_add_f32_e32 v177, v177, v178
	v_add_f32_e32 v176, v176, v177
	v_mul_f32_e32 v177, v124, v124
	v_mul_f32_e32 v178, v126, v126
	v_fmac_f32_e32 v177, v125, v125
	v_fmac_f32_e32 v178, v127, v127
	v_add_f32_e32 v177, v177, v178
	v_add_f32_e32 v176, v176, v177
	s_nop 1
	v_add_f32_dpp v176, v176, v176 quad_perm:[1,0,3,2] row_mask:0xf bank_mask:0xf
	s_nop 1
	v_add_f32_dpp v176, v176, v176 quad_perm:[2,3,0,1] row_mask:0xf bank_mask:0xf
	s_nop 1
	v_add_f32_dpp v176, v176, v176 row_half_mirror row_mask:0xf bank_mask:0xf
	s_nop 1
	v_add_f32_dpp v176, v176, v176 row_mirror row_mask:0xf bank_mask:0xf
	ds_bpermute_b32 v177, v201, v176
	s_waitcnt lgkmcnt(0)
	v_add_f32_e32 v176, v176, v177
	ds_bpermute_b32 v177, v202, v176
	s_waitcnt lgkmcnt(0)
; __device__ __forceinline__ unsigned cvt_pk_bf16(float lo, float hi) { unsigned r; asm volatile("v_cvt_pk_bf16_f32 %0, %1, %2" : "=v"(r) : "v"(lo), "v"(hi)); return r; }
; __device__ __forceinline__ void p1_rows(const Args& A, int lane, int wave) {
;     ...
;         for (int j = 0; j < 4; ++j) s += (v[j][0] * v[j][0] + v[j][1] * v[j][1]) + (v[j][2] * v[j][2] + v[j][3] * v[j][3]);
;         const float rstd = 1.0f / sqrtf(wave_sum(s) * (1.0f / DM) + RMS_EPS);
;         u32x2* o8 = (u32x2*)(HB + (size_t)m * DM) + lane;
; #pragma unroll
;         for (int j = 0; j < 4; ++j) { const int c = 4 * lane + 256 * j;
;             const f32x4 g = *(const f32x4*)(A.g_ffn1 + c), sc = *(const f32x4*)(mods + (size_t)b * NMODC + MOD_SC1 * DM + c), sh = *(const f32x4*)(mods + (size_t)b * NMODC + MOD_SH1 * DM + c);
;             const f32x4 h = (v[j] * rstd) * g * (sc + 1.0f) + sh;
;             u32x2 w; w.x = pg8::cvt_pk_bf16(h[0], h[1]); w.y = pg8::cvt_pk_bf16(h[2], h[3]); o8[64 * j] = w; }
	v_add_f32_e32 v176, v176, v177
	v_fmamk_f32 v176, v176, 0x3a800000, v204
	v_mul_f32_e32 v179, 0x4f800000, v176
	v_cmp_gt_f32_e32 vcc, s20, v176
	s_nop 1
	v_cndmask_b32_e32 v176, v176, v179, vcc
	v_sqrt_f32_e32 v179, v176
	s_nop 0
	v_add_u32_e32 v180, -1, v179
	v_add_u32_e32 v181, 1, v179
	v_fma_f32 v182, -v180, v179, v176
	v_fma_f32 v183, -v181, v179, v176
	v_cmp_ge_f32_e64 s[0:1], 0, v182
	s_nop 1
	v_cndmask_b32_e64 v179, v179, v180, s[0:1]
	v_cmp_lt_f32_e64 s[0:1], 0, v183
	s_nop 1
	v_cndmask_b32_e64 v179, v179, v181, s[0:1]
	v_mul_f32_e32 v180, 0x37800000, v179
	v_cndmask_b32_e32 v179, v179, v180, vcc
	v_cmp_class_f32_e32 vcc, v176, v203
	s_nop 1
	v_cndmask_b32_e32 v176, v179, v176, vcc
	v_div_scale_f32 v179, s[0:1], v176, v176, 1.0
	v_rcp_f32_e32 v180, v179
	v_div_scale_f32 v181, vcc, 1.0, v176, 1.0
	v_fma_f32 v182, -v179, v180, 1.0
	v_fmac_f32_e32 v180, v182, v180
	v_mul_f32_e32 v182, v181, v180
	v_fma_f32 v183, -v179, v182, v181
	v_fmac_f32_e32 v182, v183, v180
	v_fma_f32 v179, -v179, v182, v181
	v_div_fmas_f32 v179, v179, v180, v182
	v_div_fixup_f32 v206, v179, v176, 1.0
	v_pk_mul_f32 v[112:113], v[112:113], v[206:207] op_sel_hi:[1,0]
	v_pk_mul_f32 v[114:115], v[114:115], v[206:207] op_sel_hi:[1,0]
	v_pk_mul_f32 v[112:113], v[64:65], v[112:113]
	v_pk_mul_f32 v[114:115], v[66:67], v[114:115]
	v_pk_fma_f32 v[112:113], v[80:81], v[112:113], v[96:97]
	v_pk_fma_f32 v[114:115], v[82:83], v[114:115], v[98:99]
	v_cvt_pk_bf16_f32 v184, v112, v113
	v_cvt_pk_bf16_f32 v185, v114, v115
	global_store_dwordx2 v34, v[184:185], s[16:17]
	v_pk_mul_f32 v[116:117], v[116:117], v[206:207] op_sel_hi:[1,0]
	v_pk_mul_f32 v[118:119], v[118:119], v[206:207] op_sel_hi:[1,0]
	v_pk_mul_f32 v[116:117], v[68:69], v[116:117]
	v_pk_mul_f32 v[118:119], v[70:71], v[118:119]
	v_pk_fma_f32 v[116:117], v[84:85], v[116:117], v[100:101]
	v_pk_fma_f32 v[118:119], v[86:87], v[118:119], v[102:103]
	v_cvt_pk_bf16_f32 v186, v116, v117
	v_cvt_pk_bf16_f32 v187, v118, v119
	global_store_dwordx2 v34, v[186:187], s[16:17] offset:512
	v_pk_mul_f32 v[120:121], v[120:121], v[206:207] op_sel_hi:[1,0]
	v_pk_mul_f32 v[122:123], v[122:123], v[206:207] op_sel_hi:[1,0]
	v_pk_mul_f32 v[120:121], v[72:73], v[120:121]
	v_pk_mul_f32 v[122:123], v[74:75], v[122:123]
	v_pk_fma_f32 v[120:121], v[88:89], v[120:121], v[104:105]
	v_pk_fma_f32 v[122:123], v[90:91], v[122:123], v[106:107]
	v_cvt_pk_bf16_f32 v188, v120, v121
	v_cvt_pk_bf16_f32 v189, v122, v123
	global_store_dwordx2 v34, v[188:189], s[16:17] offset:1024
	v_pk_mul_f32 v[124:125], v[124:125], v[206:207] op_sel_hi:[1,0]
	v_pk_mul_f32 v[126:127], v[126:127], v[206:207] op_sel_hi:[1,0]
	v_pk_mul_f32 v[124:125], v[76:77], v[124:125]
	v_pk_mul_f32 v[126:127], v[78:79], v[126:127]
	v_pk_fma_f32 v[124:125], v[92:93], v[124:125], v[108:109]
	v_pk_fma_f32 v[126:127], v[94:95], v[126:127], v[110:111]
	v_cvt_pk_bf16_f32 v190, v124, v125
	v_cvt_pk_bf16_f32 v191, v126, v127
	global_store_dwordx2 v34, v[190:191], s[16:17] offset:1536
	s_add_u32 s16, s16, 0x800
	s_addc_u32 s17, s17, 0
	s_waitcnt vmcnt(20)
	v_mul_f32_e32 v177, v128, v128
	v_mul_f32_e32 v178, v130, v130
	v_fmac_f32_e32 v177, v129, v129
	v_fmac_f32_e32 v178, v131, v131
	v_add_f32_e32 v176, v177, v178
	v_mul_f32_e32 v177, v132, v132
	v_mul_f32_e32 v178, v134, v134
	v_fmac_f32_e32 v177, v133, v133
	v_fmac_f32_e32 v178, v135, v135
	v_add_f32_e32 v177, v177, v178
	v_add_f32_e32 v176, v176, v177
	v_mul_f32_e32 v177, v136, v136
	v_mul_f32_e32 v178, v138, v138
	v_fmac_f32_e32 v177, v137, v137
	v_fmac_f32_e32 v178, v139, v139
	v_add_f32_e32 v177, v177, v178
	v_add_f32_e32 v176, v176, v177
	v_mul_f32_e32 v177, v140, v140
	v_mul_f32_e32 v178, v142, v142
	v_fmac_f32_e32 v177, v141, v141
	v_fmac_f32_e32 v178, v143, v143
	v_add_f32_e32 v177, v177, v178
	v_add_f32_e32 v176, v176, v177
	s_nop 1
	v_add_f32_dpp v176, v176, v176 quad_perm:[1,0,3,2] row_mask:0xf bank_mask:0xf
	s_nop 1
	v_add_f32_dpp v176, v176, v176 quad_perm:[2,3,0,1] row_mask:0xf bank_mask:0xf
	s_nop 1
	v_add_f32_dpp v176, v176, v176 row_half_mirror row_mask:0xf bank_mask:0xf
	s_nop 1
	v_add_f32_dpp v176, v176, v176 row_mirror row_mask:0xf bank_mask:0xf
	ds_bpermute_b32 v177, v201, v176
	s_waitcnt lgkmcnt(0)
	v_add_f32_e32 v176, v176, v177
	ds_bpermute_b32 v177, v202, v176
	s_waitcnt lgkmcnt(0)
; __device__ __forceinline__ unsigned cvt_pk_bf16(float lo, float hi) { unsigned r; asm volatile("v_cvt_pk_bf16_f32 %0, %1, %2" : "=v"(r) : "v"(lo), "v"(hi)); return r; }
; __device__ __forceinline__ void p1_rows(const Args& A, int lane, int wave) {
;     ...
;         for (int j = 0; j < 4; ++j) s += (v[j][0] * v[j][0] + v[j][1] * v[j][1]) + (v[j][2] * v[j][2] + v[j][3] * v[j][3]);
;         const float rstd = 1.0f / sqrtf(wave_sum(s) * (1.0f / DM) + RMS_EPS);
;         u32x2* o8 = (u32x2*)(HB + (size_t)m * DM) + lane;
; #pragma unroll
;         for (int j = 0; j < 4; ++j) { const int c = 4 * lane + 256 * j;
;             const f32x4 g = *(const f32x4*)(A.g_ffn1 + c), sc = *(const f32x4*)(mods + (size_t)b * NMODC + MOD_SC1 * DM + c), sh = *(const f32x4*)(mods + (size_t)b * NMODC + MOD_SH1 * DM + c);
;             const f32x4 h = (v[j] * rstd) * g * (sc + 1.0f) + sh;
;             u32x2 w; w.x = pg8::cvt_pk_bf16(h[0], h[1]); w.y = pg8::cvt_pk_bf16(h[2], h[3]); o8[64 * j] = w; }
	v_add_f32_e32 v176, v176, v177
	v_fmamk_f32 v176, v176, 0x3a800000, v204
	v_mul_f32_e32 v179, 0x4f800000, v176
	v_cmp_gt_f32_e32 vcc, s20, v176
	s_nop 1
	v_cndmask_b32_e32 v176, v176, v179, vcc
	v_sqrt_f32_e32 v179, v176
	s_nop 0
	v_add_u32_e32 v180, -1, v179
	v_add_u32_e32 v181, 1, v179
	v_fma_f32 v182, -v180, v179, v176
	v_fma_f32 v183, -v181, v179, v176
	v_cmp_ge_f32_e64 s[0:1], 0, v182
	s_nop 1
	v_cndmask_b32_e64 v179, v179, v180, s[0:1]
	v_cmp_lt_f32_e64 s[0:1], 0, v183
	s_nop 1
	v_cndmask_b32_e64 v179, v179, v181, s[0:1]
	v_mul_f32_e32 v180, 0x37800000, v179
	v_cndmask_b32_e32 v179, v179, v180, vcc
	v_cmp_class_f32_e32 vcc, v176, v203
	s_nop 1
	v_cndmask_b32_e32 v176, v179, v176, vcc
	v_div_scale_f32 v179, s[0:1], v176, v176, 1.0
	v_rcp_f32_e32 v180, v179
	v_div_scale_f32 v181, vcc, 1.0, v176, 1.0
	v_fma_f32 v182, -v179, v180, 1.0
	v_fmac_f32_e32 v180, v182, v180
	v_mul_f32_e32 v182, v181, v180
	v_fma_f32 v183, -v179, v182, v181
	v_fmac_f32_e32 v182, v183, v180
	v_fma_f32 v179, -v179, v182, v181
	v_div_fmas_f32 v179, v179, v180, v182
	v_div_fixup_f32 v206, v179, v176, 1.0
	v_pk_mul_f32 v[128:129], v[128:129], v[206:207] op_sel_hi:[1,0]
	v_pk_mul_f32 v[130:131], v[130:131], v[206:207] op_sel_hi:[1,0]
	v_pk_mul_f32 v[128:129], v[64:65], v[128:129]
	v_pk_mul_f32 v[130:131], v[66:67], v[130:131]
	v_pk_fma_f32 v[128:129], v[80:81], v[128:129], v[96:97]
	v_pk_fma_f32 v[130:131], v[82:83], v[130:131], v[98:99]
	v_cvt_pk_bf16_f32 v192, v128, v129
	v_cvt_pk_bf16_f32 v193, v130, v131
	global_store_dwordx2 v34, v[192:193], s[16:17]
	v_pk_mul_f32 v[132:133], v[132:133], v[206:207] op_sel_hi:[1,0]
	v_pk_mul_f32 v[134:135], v[134:135], v[206:207] op_sel_hi:[1,0]
	v_pk_mul_f32 v[132:133], v[68:69], v[132:133]
	v_pk_mul_f32 v[134:135], v[70:71], v[134:135]
	v_pk_fma_f32 v[132:133], v[84:85], v[132:133], v[100:101]
	v_pk_fma_f32 v[134:135], v[86:87], v[134:135], v[102:103]
	v_cvt_pk_bf16_f32 v194, v132, v133
	v_cvt_pk_bf16_f32 v195, v134, v135
	global_store_dwordx2 v34, v[194:195], s[16:17] offset:512
	v_pk_mul_f32 v[136:137], v[136:137], v[206:207] op_sel_hi:[1,0]
	v_pk_mul_f32 v[138:139], v[138:139], v[206:207] op_sel_hi:[1,0]
	v_pk_mul_f32 v[136:137], v[72:73], v[136:137]
	v_pk_mul_f32 v[138:139], v[74:75], v[138:139]
	v_pk_fma_f32 v[136:137], v[88:89], v[136:137], v[104:105]
	v_pk_fma_f32 v[138:139], v[90:91], v[138:139], v[106:107]
	v_cvt_pk_bf16_f32 v196, v136, v137
	v_cvt_pk_bf16_f32 v197, v138, v139
	global_store_dwordx2 v34, v[196:197], s[16:17] offset:1024
	v_pk_mul_f32 v[140:141], v[140:141], v[206:207] op_sel_hi:[1,0]
	v_pk_mul_f32 v[142:143], v[142:143], v[206:207] op_sel_hi:[1,0]
	v_pk_mul_f32 v[140:141], v[76:77], v[140:141]
	v_pk_mul_f32 v[142:143], v[78:79], v[142:143]
	v_pk_fma_f32 v[140:141], v[92:93], v[140:141], v[108:109]
	v_pk_fma_f32 v[142:143], v[94:95], v[142:143], v[110:111]
	v_cvt_pk_bf16_f32 v198, v140, v141
	v_cvt_pk_bf16_f32 v199, v142, v143
	global_store_dwordx2 v34, v[198:199], s[16:17] offset:1536
	s_add_u32 s16, s16, 0x800
	s_addc_u32 s17, s17, 0
	s_waitcnt vmcnt(16)
	v_mul_f32_e32 v177, v144, v144
	v_mul_f32_e32 v178, v146, v146
	v_fmac_f32_e32 v177, v145, v145
	v_fmac_f32_e32 v178, v147, v147
	v_add_f32_e32 v176, v177, v178
	v_mul_f32_e32 v177, v148, v148
	v_mul_f32_e32 v178, v150, v150
	v_fmac_f32_e32 v177, v149, v149
	v_fmac_f32_e32 v178, v151, v151
	v_add_f32_e32 v177, v177, v178
	v_add_f32_e32 v176, v176, v177
	v_mul_f32_e32 v177, v152, v152
	v_mul_f32_e32 v178, v154, v154
	v_fmac_f32_e32 v177, v153, v153
	v_fmac_f32_e32 v178, v155, v155
	v_add_f32_e32 v177, v177, v178
	v_add_f32_e32 v176, v176, v177
	v_mul_f32_e32 v177, v156, v156
	v_mul_f32_e32 v178, v158, v158
	v_fmac_f32_e32 v177, v157, v157
	v_fmac_f32_e32 v178, v159, v159
	v_add_f32_e32 v177, v177, v178
	v_add_f32_e32 v176, v176, v177
	s_nop 1
	v_add_f32_dpp v176, v176, v176 quad_perm:[1,0,3,2] row_mask:0xf bank_mask:0xf
	s_nop 1
	v_add_f32_dpp v176, v176, v176 quad_perm:[2,3,0,1] row_mask:0xf bank_mask:0xf
	s_nop 1
	v_add_f32_dpp v176, v176, v176 row_half_mirror row_mask:0xf bank_mask:0xf
	s_nop 1
	v_add_f32_dpp v176, v176, v176 row_mirror row_mask:0xf bank_mask:0xf
	ds_bpermute_b32 v177, v201, v176
	s_waitcnt lgkmcnt(0)
	v_add_f32_e32 v176, v176, v177
	ds_bpermute_b32 v177, v202, v176
	s_waitcnt lgkmcnt(0)
; __device__ __forceinline__ unsigned cvt_pk_bf16(float lo, float hi) { unsigned r; asm volatile("v_cvt_pk_bf16_f32 %0, %1, %2" : "=v"(r) : "v"(lo), "v"(hi)); return r; }
; __device__ __forceinline__ void p1_rows(const Args& A, int lane, int wave) {
;     ...
; #pragma unroll
;             for (int j = 0; j < 4; ++j) nx[j] = ((const f32x4*)(A.x + (size_t)(m + NGW) * DM) + lane)[64 * j]; }
; #pragma unroll
;         for (int j = 0; j < 4; ++j) s += (v[j][0] * v[j][0] + v[j][1] * v[j][1]) + (v[j][2] * v[j][2] + v[j][3] * v[j][3]);
;         const float rstd = 1.0f / sqrtf(wave_sum(s) * (1.0f / DM) + RMS_EPS);
;         u32x2* o8 = (u32x2*)(HB + (size_t)m * DM) + lane;
; #pragma unroll
;         for (int j = 0; j < 4; ++j) { const int c = 4 * lane + 256 * j;
;             const f32x4 g = *(const f32x4*)(A.g_ffn1 + c), sc = *(const f32x4*)(mods + (size_t)b * NMODC + MOD_SC1 * DM + c), sh = *(const f32x4*)(mods + (size_t)b * NMODC + MOD_SH1 * DM + c);
;             const f32x4 h = (v[j] * rstd) * g * (sc + 1.0f) + sh;
;             u32x2 w; w.x = pg8::cvt_pk_bf16(h[0], h[1]); w.y = pg8::cvt_pk_bf16(h[2], h[3]); o8[64 * j] = w; }
	v_add_f32_e32 v176, v176, v177
	v_fmamk_f32 v176, v176, 0x3a800000, v204
	v_mul_f32_e32 v179, 0x4f800000, v176
	v_cmp_gt_f32_e32 vcc, s20, v176
	s_nop 1
	v_cndmask_b32_e32 v176, v176, v179, vcc
	v_sqrt_f32_e32 v179, v176
	s_nop 0
	v_add_u32_e32 v180, -1, v179
	v_add_u32_e32 v181, 1, v179
	v_fma_f32 v182, -v180, v179, v176
	v_fma_f32 v183, -v181, v179, v176
	v_cmp_ge_f32_e64 s[0:1], 0, v182
	s_nop 1
	v_cndmask_b32_e64 v179, v179, v180, s[0:1]
	v_cmp_lt_f32_e64 s[0:1], 0, v183
	s_nop 1
	v_cndmask_b32_e64 v179, v179, v181, s[0:1]
	v_mul_f32_e32 v180, 0x37800000, v179
	v_cndmask_b32_e32 v179, v179, v180, vcc
	v_cmp_class_f32_e32 vcc, v176, v203
	s_nop 1
	v_cndmask_b32_e32 v176, v179, v176, vcc
	v_div_scale_f32 v179, s[0:1], v176, v176, 1.0
	v_rcp_f32_e32 v180, v179
	v_div_scale_f32 v181, vcc, 1.0, v176, 1.0
	v_fma_f32 v182, -v179, v180, 1.0
	v_fmac_f32_e32 v180, v182, v180
	v_mul_f32_e32 v182, v181, v180
	v_fma_f32 v183, -v179, v182, v181
	v_fmac_f32_e32 v182, v183, v180
	v_fma_f32 v179, -v179, v182, v181
	v_div_fmas_f32 v179, v179, v180, v182
	v_div_fixup_f32 v206, v179, v176, 1.0
	v_pk_mul_f32 v[144:145], v[144:145], v[206:207] op_sel_hi:[1,0]
	v_pk_mul_f32 v[146:147], v[146:147], v[206:207] op_sel_hi:[1,0]
	v_pk_mul_f32 v[144:145], v[64:65], v[144:145]
	v_pk_mul_f32 v[146:147], v[66:67], v[146:147]
	v_pk_fma_f32 v[144:145], v[80:81], v[144:145], v[96:97]
	v_pk_fma_f32 v[146:147], v[82:83], v[146:147], v[98:99]
	v_cvt_pk_bf16_f32 v184, v144, v145
	v_cvt_pk_bf16_f32 v185, v146, v147
	global_store_dwordx2 v34, v[184:185], s[16:17]
	v_pk_mul_f32 v[148:149], v[148:149], v[206:207] op_sel_hi:[1,0]
	v_pk_mul_f32 v[150:151], v[150:151], v[206:207] op_sel_hi:[1,0]
	v_pk_mul_f32 v[148:149], v[68:69], v[148:149]
	v_pk_mul_f32 v[150:151], v[70:71], v[150:151]
	v_pk_fma_f32 v[148:149], v[84:85], v[148:149], v[100:101]
	v_pk_fma_f32 v[150:151], v[86:87], v[150:151], v[102:103]
	v_cvt_pk_bf16_f32 v186, v148, v149
	v_cvt_pk_bf16_f32 v187, v150, v151
	global_store_dwordx2 v34, v[186:187], s[16:17] offset:512
	v_pk_mul_f32 v[152:153], v[152:153], v[206:207] op_sel_hi:[1,0]
	v_pk_mul_f32 v[154:155], v[154:155], v[206:207] op_sel_hi:[1,0]
	v_pk_mul_f32 v[152:153], v[72:73], v[152:153]
	v_pk_mul_f32 v[154:155], v[74:75], v[154:155]
	v_pk_fma_f32 v[152:153], v[88:89], v[152:153], v[104:105]
	v_pk_fma_f32 v[154:155], v[90:91], v[154:155], v[106:107]
	v_cvt_pk_bf16_f32 v188, v152, v153
	v_cvt_pk_bf16_f32 v189, v154, v155
	global_store_dwordx2 v34, v[188:189], s[16:17] offset:1024
	v_pk_mul_f32 v[156:157], v[156:157], v[206:207] op_sel_hi:[1,0]
	v_pk_mul_f32 v[158:159], v[158:159], v[206:207] op_sel_hi:[1,0]
	v_pk_mul_f32 v[156:157], v[76:77], v[156:157]
	v_pk_mul_f32 v[158:159], v[78:79], v[158:159]
	v_pk_fma_f32 v[156:157], v[92:93], v[156:157], v[108:109]
	v_pk_fma_f32 v[158:159], v[94:95], v[158:159], v[110:111]
	v_cvt_pk_bf16_f32 v190, v156, v157
	v_cvt_pk_bf16_f32 v191, v158, v159
	global_store_dwordx2 v34, v[190:191], s[16:17] offset:1536
	s_add_u32 s16, s16, 0x800
	s_addc_u32 s17, s17, 0
	s_waitcnt vmcnt(12)
	v_mul_f32_e32 v177, v160, v160
	v_mul_f32_e32 v178, v162, v162
	v_fmac_f32_e32 v177, v161, v161
	v_fmac_f32_e32 v178, v163, v163
	v_add_f32_e32 v176, v177, v178
	v_mul_f32_e32 v177, v164, v164
	v_mul_f32_e32 v178, v166, v166
	v_fmac_f32_e32 v177, v165, v165
	v_fmac_f32_e32 v178, v167, v167
	v_add_f32_e32 v177, v177, v178
	v_add_f32_e32 v176, v176, v177
	v_mul_f32_e32 v177, v168, v168
	v_mul_f32_e32 v178, v170, v170
	v_fmac_f32_e32 v177, v169, v169
	v_fmac_f32_e32 v178, v171, v171
	v_add_f32_e32 v177, v177, v178
	v_add_f32_e32 v176, v176, v177
	v_mul_f32_e32 v177, v172, v172
	v_mul_f32_e32 v178, v174, v174
	v_fmac_f32_e32 v177, v173, v173
	v_fmac_f32_e32 v178, v175, v175
	v_add_f32_e32 v177, v177, v178
	v_add_f32_e32 v176, v176, v177
	s_nop 1
	v_add_f32_dpp v176, v176, v176 quad_perm:[1,0,3,2] row_mask:0xf bank_mask:0xf
	s_nop 1
	v_add_f32_dpp v176, v176, v176 quad_perm:[2,3,0,1] row_mask:0xf bank_mask:0xf
	s_nop 1
	v_add_f32_dpp v176, v176, v176 row_half_mirror row_mask:0xf bank_mask:0xf
	s_nop 1
	v_add_f32_dpp v176, v176, v176 row_mirror row_mask:0xf bank_mask:0xf
	ds_bpermute_b32 v177, v201, v176
	s_waitcnt lgkmcnt(0)
; __device__ __forceinline__ unsigned cvt_pk_bf16(float lo, float hi) { unsigned r; asm volatile("v_cvt_pk_bf16_f32 %0, %1, %2" : "=v"(r) : "v"(lo), "v"(hi)); return r; }
; __device__ __forceinline__ void p1_rows(const Args& A, int lane, int wave) {
;     ...
;         for (int j = 0; j < 4; ++j) s += (v[j][0] * v[j][0] + v[j][1] * v[j][1]) + (v[j][2] * v[j][2] + v[j][3] * v[j][3]);
;         const float rstd = 1.0f / sqrtf(wave_sum(s) * (1.0f / DM) + RMS_EPS);
;         u32x2* o8 = (u32x2*)(HB + (size_t)m * DM) + lane;
; #pragma unroll
;         for (int j = 0; j < 4; ++j) { const int c = 4 * lane + 256 * j;
;             const f32x4 g = *(const f32x4*)(A.g_ffn1 + c), sc = *(const f32x4*)(mods + (size_t)b * NMODC + MOD_SC1 * DM + c), sh = *(const f32x4*)(mods + (size_t)b * NMODC + MOD_SH1 * DM + c);
;             const f32x4 h = (v[j] * rstd) * g * (sc + 1.0f) + sh;
;             u32x2 w; w.x = pg8::cvt_pk_bf16(h[0], h[1]); w.y = pg8::cvt_pk_bf16(h[2], h[3]); o8[64 * j] = w; }
	v_add_f32_e32 v176, v176, v177
	ds_bpermute_b32 v177, v202, v176
	s_waitcnt lgkmcnt(0)
	v_add_f32_e32 v176, v176, v177
	v_fmamk_f32 v176, v176, 0x3a800000, v204
	v_mul_f32_e32 v179, 0x4f800000, v176
	v_cmp_gt_f32_e32 vcc, s20, v176
	s_nop 1
	v_cndmask_b32_e32 v176, v176, v179, vcc
	v_sqrt_f32_e32 v179, v176
	s_nop 0
	v_add_u32_e32 v180, -1, v179
	v_add_u32_e32 v181, 1, v179
	v_fma_f32 v182, -v180, v179, v176
	v_fma_f32 v183, -v181, v179, v176
	v_cmp_ge_f32_e64 s[0:1], 0, v182
	s_nop 1
	v_cndmask_b32_e64 v179, v179, v180, s[0:1]
	v_cmp_lt_f32_e64 s[0:1], 0, v183
	s_nop 1
	v_cndmask_b32_e64 v179, v179, v181, s[0:1]
	v_mul_f32_e32 v180, 0x37800000, v179
	v_cndmask_b32_e32 v179, v179, v180, vcc
	v_cmp_class_f32_e32 vcc, v176, v203
	s_nop 1
	v_cndmask_b32_e32 v176, v179, v176, vcc
	v_div_scale_f32 v179, s[0:1], v176, v176, 1.0
	v_rcp_f32_e32 v180, v179
	v_div_scale_f32 v181, vcc, 1.0, v176, 1.0
	v_fma_f32 v182, -v179, v180, 1.0
	v_fmac_f32_e32 v180, v182, v180
	v_mul_f32_e32 v182, v181, v180
	v_fma_f32 v183, -v179, v182, v181
	v_fmac_f32_e32 v182, v183, v180
	v_fma_f32 v179, -v179, v182, v181
	v_div_fmas_f32 v179, v179, v180, v182
	v_div_fixup_f32 v206, v179, v176, 1.0
	v_pk_mul_f32 v[160:161], v[160:161], v[206:207] op_sel_hi:[1,0]
	v_pk_mul_f32 v[162:163], v[162:163], v[206:207] op_sel_hi:[1,0]
	v_pk_mul_f32 v[160:161], v[64:65], v[160:161]
	v_pk_mul_f32 v[162:163], v[66:67], v[162:163]
	v_pk_fma_f32 v[160:161], v[80:81], v[160:161], v[96:97]
	v_pk_fma_f32 v[162:163], v[82:83], v[162:163], v[98:99]
	v_cvt_pk_bf16_f32 v192, v160, v161
	v_cvt_pk_bf16_f32 v193, v162, v163
	global_store_dwordx2 v34, v[192:193], s[16:17]
	v_pk_mul_f32 v[164:165], v[164:165], v[206:207] op_sel_hi:[1,0]
	v_pk_mul_f32 v[166:167], v[166:167], v[206:207] op_sel_hi:[1,0]
	v_pk_mul_f32 v[164:165], v[68:69], v[164:165]
	v_pk_mul_f32 v[166:167], v[70:71], v[166:167]
	v_pk_fma_f32 v[164:165], v[84:85], v[164:165], v[100:101]
	v_pk_fma_f32 v[166:167], v[86:87], v[166:167], v[102:103]
	v_cvt_pk_bf16_f32 v194, v164, v165
	v_cvt_pk_bf16_f32 v195, v166, v167
	global_store_dwordx2 v34, v[194:195], s[16:17] offset:512
	v_pk_mul_f32 v[168:169], v[168:169], v[206:207] op_sel_hi:[1,0]
	v_pk_mul_f32 v[170:171], v[170:171], v[206:207] op_sel_hi:[1,0]
	v_pk_mul_f32 v[168:169], v[72:73], v[168:169]
	v_pk_mul_f32 v[170:171], v[74:75], v[170:171]
	v_pk_fma_f32 v[168:169], v[88:89], v[168:169], v[104:105]
	v_pk_fma_f32 v[170:171], v[90:91], v[170:171], v[106:107]
	v_cvt_pk_bf16_f32 v196, v168, v169
	v_cvt_pk_bf16_f32 v197, v170, v171
	global_store_dwordx2 v34, v[196:197], s[16:17] offset:1024
	v_pk_mul_f32 v[172:173], v[172:173], v[206:207] op_sel_hi:[1,0]
	v_pk_mul_f32 v[174:175], v[174:175], v[206:207] op_sel_hi:[1,0]
	v_pk_mul_f32 v[172:173], v[76:77], v[172:173]
	v_pk_mul_f32 v[174:175], v[78:79], v[174:175]
	v_pk_fma_f32 v[172:173], v[92:93], v[172:173], v[108:109]
	v_pk_fma_f32 v[174:175], v[94:95], v[174:175], v[110:111]
	v_cvt_pk_bf16_f32 v198, v172, v173
	v_cvt_pk_bf16_f32 v199, v174, v175
	global_store_dwordx2 v34, v[198:199], s[16:17] offset:1536
	s_add_u32 s16, s16, 0x800
	s_addc_u32 s17, s17, 0
